# attention: zero-reference fast path (when a row block's first 32-key max is within +-64 the softmax reference snaps to 0 and a copy of the tile body without the 64 score-minus-reference subtractions r
# speedup vs baseline: 1.0245x; 1.0177x over previous
; #define ATT_LAS __attribute__((address_space(3)))
; __device__ __forceinline__ void attn_unit(ATT_LAS unsigned char* lds, const bf16_t* Qg, const bf16_t* Kg, const bf16_t* Vg, bf16_t* Og, int b, int head, int qb, float lam, const float* subg) {
;     int tid = threadIdx.x; asm volatile("" : "+v"(tid));
;     const int lane = tid & 63, r = lane & 31, h = lane >> 5;
;     const int w = __builtin_amdgcn_readfirstlane(tid >> 6);
;     const size_t rowbase = (size_t)b * SEQ; const int q0 = qb * 256, NT = (q0 + 256) >> 6;
;     const int wq = (w < 4) ? w : 11 - w;
;     const char* Kt = (const char*)(Kg + rowbase * PITCH + head * 128);
;     const char* Vt = (const char*)(Vg + rowbase * PITCH + head * 128);
;     unsigned ksrc[2], vsrc[2];
; #pragma unroll
;     for (int i = 0; i < 2; ++i) { const int ii = w * 2 + i;
;         { const int row = 4 * ii + (lane >> 4), pc = lane & 15; ksrc[i] = (unsigned)(row * 2048 + ((pc ^ (row & 15)) << 4)); }
;         { const int row = 8 * (ii >> 1) + ((lane >> 2) & 7), ch = 4 * (2 * (ii & 1) + (lane >> 5)) + ((lane & 3) ^ ((row >> 2) & 3)); vsrc[i] = (unsigned)(row * 2048 + ch * 16); } }
;     const unsigned ldsb = (unsigned)(uintptr_t)lds;
;     ...
;     ATT_STAGE(0, 0);
;     { const char* Qw = (const char*)(Qg + (rowbase + q0 + wq * 32) * PITCH + head * 128);
; #pragma unroll
;       for (int i = 0; i < 8; ++i) { const int row = 4 * i + (lane >> 4), pc = lane & 15;
;           glds16(Qw, (unsigned)(row * 2048 + ((pc ^ (row & 15)) << 4)), (unsigned)__builtin_amdgcn_readfirstlane(ldsb + QBUF + w * 8192 + i * 1024)); } }
;     const ATT_LAS unsigned char* qbase = lds + QBUF + w * 8192;
;     int kaddr[4], vaddr[2];
; #pragma unroll
;     for (int ds = 0; ds < 4; ++ds) kaddr[ds] = koffs(r, 2 * ds + h);
;     { const int q = (lane & 15) >> 2, p = lane & 3, blk = (lane >> 4) & 1;
; #pragma unroll
;       for (int sub = 0; sub < 2; ++sub) vaddr[sub] = voffs(8 * sub + 4 * h + q, 2 * blk + (p >> 1)) + 8 * (p & 1); }
;     ATT_LAS float* wsf = (ATT_LAS float*)(lds + WSF + w * 512);
.LBB0_285:
	s_mov_b32 s100, 0x42800000
	v_mov_b32_e32 v0, v190
	s_xor_b64 s[88:89], s[2:3], -1
	v_readfirstlane_b32 s4, v0
	s_ashr_i32 s4, s4, 6
	s_and_b64 s[2:3], s[2:3], exec
	s_cselect_b32 s5, s1, s0
	s_lshl_b32 s3, s4, 3
	v_lshrrev_b32_e32 v5, 2, v0
	v_and_or_b32 v5, v5, 7, s3
	v_bfe_u32 v3, v0, 4, 2
	v_lshrrev_b32_e32 v6, 2, v5
	v_or_b32_e32 v4, s3, v3
	v_xor_b32_e32 v6, v6, v0
	v_bitop3_b32 v8, s3, v0, v3 bitop3:0x36
	v_bfe_u32 v195, v0, 5, 1
	v_lshlrev_b32_e32 v7, 11, v4
	v_lshlrev_b32_e32 v8, 4, v8
	v_lshlrev_b32_e32 v6, 4, v6
	s_lshl_b32 s77, s4, 11
	s_add_i32 s2, s5, 0x100
	v_lshlrev_b32_e32 v5, 11, v5
	v_and_or_b32 v198, v8, s97, v7
	v_lshlrev_b32_e32 v7, 6, v195
	v_and_b32_e32 v6, 48, v6
	s_add_i32 s6, 0, 0x8000
	s_or_b32 s50, s77, 0x400
	s_lshr_b32 s76, s2, 6
	s_sub_i32 s2, 11, s4
	v_or3_b32 v199, v6, v7, v5
	v_or_b32_e32 v5, 4, v4
	v_bitop3_b32 v4, v4, v0, 4 bitop3:0x36
	s_add_i32 s3, s77, 0
	s_add_i32 s7, s77, s6
	s_add_i32 s8, s50, 0
	s_add_i32 s6, s50, s6
	s_mov_b32 s9, m0
	s_mov_b32 m0, s3
	s_nop 0
	global_load_lds_dwordx4 v198, s[64:65]
	s_mov_b32 m0, s9
	v_lshlrev_b32_e32 v5, 11, v5
	v_lshlrev_b32_e32 v4, 4, v4
	s_cmp_lt_i32 s4, 4
	s_mov_b32 s3, m0
	s_mov_b32 m0, s7
	s_nop 0
	global_load_lds_dwordx4 v199, s[66:67]
	s_mov_b32 m0, s3
	v_and_or_b32 v200, v4, s97, v5
	s_mov_b32 s3, m0
	s_mov_b32 m0, s8
	s_nop 0
	global_load_lds_dwordx4 v200, s[64:65]
	s_mov_b32 m0, s3
	s_cselect_b32 s2, s4, s2
	v_or_b32_e32 v201, 0x80, v199
	s_mov_b32 s3, m0
	s_mov_b32 m0, s6
	s_nop 0
	global_load_lds_dwordx4 v201, s[66:67]
	s_mov_b32 m0, s3
	s_lshl_b32 s6, s2, 5
	s_or_b32 s3, s68, s5
	s_ashr_i32 s7, s6, 31
	s_add_u32 s2, s3, s6
	s_addc_u32 s3, s69, s7
	s_lshl_b64 s[90:91], s[2:3], 10
	s_lshl_b64 s[2:3], s[2:3], 11
	s_add_u32 s2, s48, s2
	v_xor_b32_e32 v5, v3, v0
	s_addc_u32 s3, s49, s3
	v_lshlrev_b32_e32 v4, 11, v3
	v_lshlrev_b32_e32 v5, 4, v5
	s_add_u32 s2, s2, s42
	v_and_or_b32 v4, v5, s97, v4
	v_or_b32_e32 v5, 4, v3
	v_bitop3_b32 v6, v3, v0, 4 bitop3:0x36
	s_addc_u32 s3, s3, 0
	s_lshl_b32 s7, s4, 13
	v_lshlrev_b32_e32 v5, 11, v5
	v_lshlrev_b32_e32 v6, 4, v6
	s_add_i32 s51, s7, s99
	s_mov_b32 s8, m0
	s_mov_b32 m0, s51
	s_nop 0
	global_load_lds_dwordx4 v4, s[2:3]
	s_mov_b32 m0, s8
	v_and_or_b32 v5, v6, s97, v5
	s_add_i32 s7, s7, 0
	s_add_i32 s8, s7, 0x11400
	s_mov_b32 s9, m0
	s_mov_b32 m0, s8
	s_nop 0
	global_load_lds_dwordx4 v5, s[2:3]
	s_mov_b32 m0, s9
	v_or_b32_e32 v5, 8, v3
	v_bitop3_b32 v6, v3, v0, 8 bitop3:0x36
	v_lshlrev_b32_e32 v5, 11, v5
	v_lshlrev_b32_e32 v6, 4, v6
	v_and_or_b32 v5, v6, s97, v5
	s_add_i32 s8, s7, 0x11800
	s_mov_b32 s9, m0
	s_mov_b32 m0, s8
	s_nop 0
	global_load_lds_dwordx4 v5, s[2:3]
	s_mov_b32 m0, s9
	v_or_b32_e32 v5, 12, v3
	v_bitop3_b32 v6, v3, v0, 12 bitop3:0x36
	v_lshlrev_b32_e32 v5, 11, v5
	v_lshlrev_b32_e32 v6, 4, v6
	v_and_or_b32 v5, v6, s97, v5
	s_add_i32 s8, s7, 0x11c00
	s_mov_b32 s9, m0
	s_mov_b32 m0, s8
	s_nop 0
	global_load_lds_dwordx4 v5, s[2:3]
	s_mov_b32 m0, s9
	v_or_b32_e32 v4, 0x8000, v4
	s_add_i32 s8, s7, 0x12000
	s_mov_b32 s9, m0
	s_mov_b32 m0, s8
	s_nop 0
	global_load_lds_dwordx4 v4, s[2:3]
	s_mov_b32 m0, s9
	v_or_b32_e32 v4, 20, v3
	v_bitop3_b32 v5, v3, v0, 20 bitop3:0x36
	v_lshlrev_b32_e32 v4, 11, v4
	v_lshlrev_b32_e32 v5, 4, v5
	v_and_or_b32 v4, v5, s97, v4
	s_add_i32 s8, s7, 0x12400
	s_mov_b32 s9, m0
	s_mov_b32 m0, s8
	s_nop 0
	global_load_lds_dwordx4 v4, s[2:3]
	s_mov_b32 m0, s9
	v_or_b32_e32 v4, 24, v3
	v_bitop3_b32 v5, v3, v0, 24 bitop3:0x36
	v_lshlrev_b32_e32 v4, 11, v4
	v_lshlrev_b32_e32 v5, 4, v5
	v_and_or_b32 v4, v5, s97, v4
	s_add_i32 s8, s7, 0x12800
	s_mov_b32 s9, m0
	s_mov_b32 m0, s8
	s_nop 0
	global_load_lds_dwordx4 v4, s[2:3]
	s_mov_b32 m0, s9
	v_or_b32_e32 v4, 28, v3
	v_bitop3_b32 v3, v3, v0, 28 bitop3:0x36
	v_lshrrev_b32_e32 v8, 3, v0
	v_lshlrev_b32_e32 v4, 11, v4
	v_lshlrev_b32_e32 v3, 4, v3
	v_and_b32_e32 v8, 2, v8
	v_bfe_u32 v9, v0, 1, 1
	v_lshlrev_b32_e32 v11, 4, v0
	v_and_b32_e32 v2, 63, v0
	v_and_b32_e32 v196, 31, v0
	v_and_or_b32 v3, v3, s97, v4
	v_and_b32_e32 v4, 15, v0
	v_bitop3_b32 v5, v195, v0, 15 bitop3:0x78
	v_or_b32_e32 v10, v8, v9
	v_and_b32_e32 v11, 0xc0, v11
	v_lshlrev_b32_e32 v0, 3, v0
	v_bitop3_b32 v8, v8, v195, v9 bitop3:0x36
	v_lshl_or_b32 v11, v195, 8, v11
	v_and_b32_e32 v0, 8, v0
	v_lshlrev_b32_e32 v8, 4, v8
	v_or3_b32 v207, v8, v11, v0
	v_bitop3_b32 v8, v195, v10, 2 bitop3:0x36
	s_add_i32 s7, s7, 0x12c00
	s_mov_b32 s8, m0
	s_mov_b32 m0, s7
	s_nop 0
	global_load_lds_dwordx4 v3, s[2:3]
	s_mov_b32 m0, s8
	v_bitop3_b32 v6, v195, v4, 2 bitop3:0x36
	v_bitop3_b32 v7, v195, v4, 4 bitop3:0x36
	v_bitop3_b32 v4, v195, v4, 6 bitop3:0x36
	v_lshlrev_b32_e32 v8, 4, v8
	s_lshl_b32 s2, s4, 9
	s_add_i32 s5, s5, s6
	v_lshlrev_b32_e32 v3, 8, v196
	v_lshlrev_b32_e32 v5, 4, v5
	v_lshlrev_b32_e32 v6, 4, v6
	v_lshlrev_b32_e32 v7, 4, v7
	v_lshlrev_b32_e32 v4, 4, v4
	s_add_i32 s78, s2, 0
	s_waitcnt vmcnt(0)
; #define ATT_LAS __attribute__((address_space(3)))
; __device__ __forceinline__ void attn_unit(ATT_LAS unsigned char* lds, const bf16_t* Qg, const bf16_t* Kg, const bf16_t* Vg, bf16_t* Og, int b, int head, int qb, float lam, const float* subg) {
;     ...
;     const ATT_LAS unsigned char* qbase = lds + QBUF + w * 8192;
;     int kaddr[4], vaddr[2];
; #pragma unroll
;     for (int ds = 0; ds < 4; ++ds) kaddr[ds] = koffs(r, 2 * ds + h);
;     { const int q = (lane & 15) >> 2, p = lane & 3, blk = (lane >> 4) & 1;
; #pragma unroll
;       for (int sub = 0; sub < 2; ++sub) vaddr[sub] = voffs(8 * sub + 4 * h + q, 2 * blk + (p >> 1)) + 8 * (p & 1); }
;     ATT_LAS float* wsf = (ATT_LAS float*)(lds + WSF + w * 512);
;     f32x16 O1[4], O2[4];
; #pragma unroll
;     for (int db = 0; db < 4; ++db)
; #pragma unroll
;         for (int i = 0; i < 16; ++i) { O1[db][i] = 0.f; O2[db][i] = 0.f; }
;     float m1 = -1e30f, m2 = -1e30f, l1 = 0.f, l2 = 0.f;
;     asm volatile("s_waitcnt vmcnt(0)" ::: "memory"); __syncthreads();
	v_lshlrev_b32_e32 v197, 2, v195
	v_or3_b32 v213, v8, v11, v0
	v_add_u32_e32 v0, s5, v196
	v_mov_b32_e32 v14, v1
	v_mov_b32_e32 v15, v1
	v_or_b32_e32 v203, v5, v3
	v_or_b32_e32 v204, v6, v3
	v_or_b32_e32 v205, v7, v3
	v_or_b32_e32 v206, v4, v3
	s_add_i32 s78, s78, 0x10000
	v_cmp_gt_u32_e64 s[2:3], 32, v2
	v_bitop3_b32 v209, v5, s98, v3 bitop3:0x36
	v_bitop3_b32 v210, v6, s98, v3 bitop3:0x36
	v_bitop3_b32 v211, v7, s98, v3 bitop3:0x36
	v_bitop3_b32 v212, v4, s98, v3 bitop3:0x36
	v_add_u32_e32 v244, s51, v209
	v_add_u32_e32 v245, s51, v210
	v_add_u32_e32 v246, s51, v211
	v_add_u32_e32 v247, s51, v212
	v_sub_u32_e32 v214, v0, v197
	v_mov_b32_e32 v0, v1
	v_mov_b32_e32 v2, v1
	v_mov_b32_e32 v3, v1
	v_mov_b32_e32 v4, v1
	v_mov_b32_e32 v5, v1
	v_mov_b32_e32 v6, v1
	v_mov_b32_e32 v7, v1
	v_mov_b32_e32 v8, v1
	v_mov_b32_e32 v9, v1
	v_mov_b32_e32 v10, v1
	v_mov_b32_e32 v11, v1
	v_mov_b32_e32 v12, v1
	v_mov_b32_e32 v13, v1
	v_mov_b64_e32 v[32:33], v[14:15]
	v_mov_b64_e32 v[112:113], v[14:15]
	v_mov_b64_e32 v[128:129], v[14:15]
	v_mov_b64_e32 v[144:145], v[14:15]
	v_mov_b64_e32 v[48:49], v[14:15]
	v_mov_b64_e32 v[64:65], v[14:15]
	v_mov_b64_e32 v[80:81], v[14:15]
	v_mov_b64_e32 v[96:97], v[14:15]
	v_lshl_add_u32 v202, v196, 2, s78
	v_lshlrev_b32_e32 v208, 4, v195
	s_mov_b32 s79, 0
	s_sub_i32 s80, 0, s5
	v_mov_b32_e32 v215, 0xf149f2ca
	v_mov_b32_e32 v224, 0
	s_mov_b64 s[92:93], s[86:87]
	s_mov_b64 s[94:95], s[70:71]
	v_mov_b64_e32 v[30:31], v[12:13]
	v_mov_b64_e32 v[28:29], v[10:11]
	v_mov_b64_e32 v[26:27], v[8:9]
	v_mov_b64_e32 v[24:25], v[6:7]
	v_mov_b64_e32 v[22:23], v[4:5]
	v_mov_b64_e32 v[20:21], v[2:3]
	v_mov_b64_e32 v[18:19], v[0:1]
	v_mov_b64_e32 v[110:111], v[12:13]
	v_mov_b64_e32 v[108:109], v[10:11]
	v_mov_b64_e32 v[106:107], v[8:9]
	v_mov_b64_e32 v[104:105], v[6:7]
	v_mov_b64_e32 v[102:103], v[4:5]
	v_mov_b64_e32 v[100:101], v[2:3]
	v_mov_b64_e32 v[98:99], v[0:1]
	v_mov_b64_e32 v[126:127], v[12:13]
	v_mov_b64_e32 v[124:125], v[10:11]
	v_mov_b64_e32 v[122:123], v[8:9]
	v_mov_b64_e32 v[120:121], v[6:7]
	v_mov_b64_e32 v[118:119], v[4:5]
	v_mov_b64_e32 v[116:117], v[2:3]
	v_mov_b64_e32 v[114:115], v[0:1]
	v_mov_b64_e32 v[142:143], v[12:13]
	v_mov_b64_e32 v[140:141], v[10:11]
	v_mov_b64_e32 v[138:139], v[8:9]
	v_mov_b64_e32 v[136:137], v[6:7]
	v_mov_b64_e32 v[134:135], v[4:5]
	v_mov_b64_e32 v[132:133], v[2:3]
	v_mov_b64_e32 v[130:131], v[0:1]
	v_mov_b64_e32 v[46:47], v[12:13]
	v_mov_b64_e32 v[44:45], v[10:11]
	v_mov_b64_e32 v[42:43], v[8:9]
	v_mov_b64_e32 v[40:41], v[6:7]
	v_mov_b64_e32 v[38:39], v[4:5]
	v_mov_b64_e32 v[36:37], v[2:3]
	v_mov_b64_e32 v[34:35], v[0:1]
	v_mov_b64_e32 v[62:63], v[12:13]
	v_mov_b64_e32 v[60:61], v[10:11]
	v_mov_b64_e32 v[58:59], v[8:9]
	v_mov_b64_e32 v[56:57], v[6:7]
	v_mov_b64_e32 v[54:55], v[4:5]
	v_mov_b64_e32 v[52:53], v[2:3]
	v_mov_b64_e32 v[50:51], v[0:1]
	v_mov_b64_e32 v[78:79], v[12:13]
	v_mov_b64_e32 v[76:77], v[10:11]
	v_mov_b64_e32 v[74:75], v[8:9]
	v_mov_b64_e32 v[72:73], v[6:7]
	v_mov_b64_e32 v[70:71], v[4:5]
	v_mov_b64_e32 v[68:69], v[2:3]
	v_mov_b64_e32 v[66:67], v[0:1]
	v_mov_b64_e32 v[94:95], v[12:13]
	v_mov_b64_e32 v[92:93], v[10:11]
	v_mov_b64_e32 v[90:91], v[8:9]
	v_mov_b64_e32 v[88:89], v[6:7]
	v_mov_b64_e32 v[86:87], v[4:5]
	v_mov_b64_e32 v[84:85], v[2:3]
	v_mov_b64_e32 v[82:83], v[0:1]
	v_mov_b32_e32 v225, 0
	v_mov_b32_e32 v0, 0xf149f2ca
	s_barrier
	s_branch .LBB0_289

; template <bool HAS_PV, bool HAS_QK, bool C1> ...
;     s16x4 vlo[2], vhi[2]; bf16x8 ka, qa;
;     if (HAS_PV) {
; #pragma unroll
;         for (int u = 0; u < 2; ++u) { vlo[u] = vtr(vb + vaddr[0] + u * 512); vhi[u] = vtr(vb + vaddr[1] + u * 512); } }
;     if (HAS_QK) { const int ad = C1 ? sub1(kaddr[0]) : kaddr[0]; ka = *(const ATT_LAS bf16x8*)(kb + ad); qa = *(const ATT_LAS bf16x8*)(qb_ + ad);
; #pragma unroll
;         for (int i = 0; i < 16; ++i) Snext[i] = 0.f; }
;     float sa = 0.f, sb = 0.f;
; #pragma unroll
;     for (int g = 0; g < 4; ++g) {
;         s16x4 nlo[2], nhi[2]; bf16x8 nk, nq;
;         if (g < 3) {
;             if (HAS_PV) {
; #pragma unroll
;                 for (int u = 0; u < 2; ++u) { const int off = (2 * ((g + 1) & 1) + u) * 512 + ((g + 1) >> 1) * 4096; nlo[u] = vtr(vb + vaddr[0] + off); nhi[u] = vtr(vb + vaddr[1] + off); } }
;             if (HAS_QK) { const int ad = C1 ? sub1(kaddr[g + 1]) : kaddr[g + 1]; nk = *(const ATT_LAS bf16x8*)(kb + ad); nq = *(const ATT_LAS bf16x8*)(qb_ + ad); }
;         }
;         if (HAS_PV) { const bf16x8 pa = __builtin_bit_cast(bf16x8, pkin[g >> 1]);
; #pragma unroll
; __device__ __forceinline__ void apply_mask(bool MASK, f32x16& s0, int kvr, int r, int h) {
;     if (MASK) {
;         asm volatile("" ::: "memory");
;         const int d = r - 4 * h - kvr;
; #pragma unroll
;         for (int i = 0; i < 16; ++i) { if (((i & 3) + 8 * (i >> 2)) > d) s0[i] = -INFINITY; }
;     }
; }
; template <bool C1> __device__ __forceinline__ void slow_step(bool MASK, f32x16& S, const ATT_LAS unsigned char* kb, const ATT_LAS unsigned char* qbase, const int (&kaddr)[4], const int (&vaddr)[2], ...
;     l = l_saved;
;     qk_issue<C1>(S, kb, qbase, kaddr);
;     rowmax_rescale(MASK, S, O, m, l, kvr, r, h, wsf);
;     f32x16 dummy;
;     step_fused<false, false, false>(S, m, l, pk, O, pk, kb, vaddr, dummy, kb, qbase, kaddr);
; }
; __device__ __forceinline__ void tile_body(bool MASK, const ATT_LAS unsigned char* kb, const ATT_LAS unsigned char* vb, const ATT_LAS unsigned char* qbase, const int (&kaddr)[4], const int (&vaddr)[2], ...
;     f32x16 Sa, Sb; u32x4 pkA[2], pkB[2]; float ls, sm;
;     qk_issue<false>(Sa, kb, qbase, kaddr);
;     apply_mask(MASK, Sa, kvrel, r, h); ls = l1;
;     sm = step_fused<false, true, true>(Sa, m1, l1, pkA, O1, pkA, vb, vaddr, Sb, kb, qbase, kaddr);
.LBB0_291:
	s_cmp_gt_i32 s80, 31
	s_cbranch_scc1 .LBB0_288
	s_lshl_b32 s4, s4, 14
	s_add_i32 s81, s4, 0
	v_add_u32_e32 v248, s81, v209
	v_add_u32_e32 v249, s81, v210
	v_add_u32_e32 v250, s81, v211
	v_add_u32_e32 v251, s81, v212
	v_add_u32_e32 v216, s81, v203
	ds_read_b128 v[2:5], v216
	v_add_u32_e32 v217, s51, v203
	ds_read_b128 v[6:9], v217
	v_add_u32_e32 v218, s81, v204
	v_add_u32_e32 v219, s51, v204
	v_add_u32_e32 v220, s81, v205
	v_add_u32_e32 v221, s51, v205
	v_add_u32_e32 v222, s81, v206
	v_add_u32_e32 v223, s51, v206
	s_waitcnt lgkmcnt(0)
	v_mfma_f32_32x32x16_bf16 v[170:185], v[2:5], v[6:9], 0
	ds_read_b128 v[2:5], v218
	ds_read_b128 v[6:9], v219
	s_cmpk_gt_i32 s80, 0xffc1
	s_cselect_b64 s[36:37], -1, 0
	s_cmpk_lt_i32 s80, 0xffc2
	v_cmp_gt_i32_e32 vcc, 26, v214
	s_waitcnt lgkmcnt(0)
	v_mfma_f32_32x32x16_bf16 v[170:185], v[2:5], v[6:9], v[170:185]
	ds_read_b128 v[2:5], v220
	ds_read_b128 v[6:9], v221
	s_waitcnt lgkmcnt(0)
	v_mfma_f32_32x32x16_bf16 v[170:185], v[2:5], v[6:9], v[170:185]
	ds_read_b128 v[2:5], v222
	ds_read_b128 v[6:9], v223
	s_waitcnt lgkmcnt(0)
	v_mfma_f32_32x32x16_bf16 v[170:185], v[2:5], v[6:9], v[170:185]
	s_cbranch_scc1 .LBB0_296
	v_cmp_gt_i32_e64 s[34:35], 25, v214
	v_cmp_gt_i32_e64 s[28:29], 24, v214
	s_and_b64 s[34:35], vcc, s[34:35]
	v_cmp_gt_i32_e64 s[26:27], 19, v214
	s_and_b64 s[28:29], s[34:35], s[28:29]
	v_cmp_gt_i32_e64 s[24:25], 18, v214
	s_and_b64 s[26:27], s[28:29], s[26:27]
	v_cmp_gt_i32_e64 s[22:23], 17, v214
	s_and_b64 s[24:25], s[26:27], s[24:25]
	v_cmp_gt_i32_e64 s[20:21], 16, v214
	s_and_b64 s[22:23], s[24:25], s[22:23]
	v_cmp_gt_i32_e64 s[18:19], 11, v214
	s_and_b64 s[20:21], s[22:23], s[20:21]
	v_cmp_gt_i32_e64 s[16:17], 10, v214
	s_and_b64 s[18:19], s[20:21], s[18:19]
	v_cmp_gt_i32_e64 s[14:15], 9, v214
	s_and_b64 s[16:17], s[18:19], s[16:17]
	v_cmp_gt_i32_e64 s[12:13], 8, v214
	s_and_b64 s[14:15], s[16:17], s[14:15]
	v_cmp_gt_i32_e64 s[10:11], 3, v214
	s_and_b64 s[12:13], s[14:15], s[12:13]
	v_cmp_gt_i32_e64 s[8:9], 2, v214
	s_and_b64 s[10:11], s[12:13], s[10:11]
	v_cmp_gt_i32_e64 s[6:7], 1, v214
	s_and_b64 s[8:9], s[10:11], s[8:9]
	v_cmp_gt_i32_e64 s[4:5], 0, v214
	s_and_b64 s[6:7], s[8:9], s[6:7]
	s_and_b64 s[4:5], s[6:7], s[4:5]
	v_cndmask_b32_e64 v183, v183, v17, s[34:35]
	v_cndmask_b32_e64 v182, v182, v17, s[28:29]
	v_cndmask_b32_e64 v181, v181, v17, s[26:27]
	v_cndmask_b32_e64 v180, v180, v17, s[24:25]
	v_cndmask_b32_e64 v179, v179, v17, s[22:23]
	v_cndmask_b32_e64 v178, v178, v17, s[20:21]
	v_cndmask_b32_e64 v177, v177, v17, s[18:19]
	v_cndmask_b32_e64 v176, v176, v17, s[16:17]
	v_cndmask_b32_e64 v175, v175, v17, s[14:15]
	v_cndmask_b32_e64 v174, v174, v17, s[12:13]
	v_cndmask_b32_e64 v173, v173, v17, s[10:11]
	v_cndmask_b32_e64 v172, v172, v17, s[8:9]
	v_cndmask_b32_e64 v171, v171, v17, s[6:7]
	v_cndmask_b32_e64 v170, v170, v17, s[4:5]
	v_cndmask_b32_e32 v184, v184, v17, vcc
	v_cmp_gt_i32_e32 vcc, 27, v214
	s_and_saveexec_b64 s[4:5], vcc
	v_mov_b32_e32 v185, s31
	s_or_b64 exec, exec, s[4:5]
.LBB0_296:
	v_or_b32_e32 v252, v0, v215
	v_cmp_eq_u32_e32 vcc, 0, v252
	s_cmp_eq_u64 vcc, exec
	s_cbranch_scc1 .Lns_296
	ds_read_b128 v[2:5], v248
	ds_read_b128 v[6:9], v244
	s_nop 8
	v_sub_f32_e32 v16, v172, v0
	ds_read_b128 v[10:13], v249
	ds_read_b128 v[146:149], v245
	v_sub_f32_e32 v14, v170, v0
	v_exp_f32_e32 v15, v14
	v_sub_f32_e32 v14, v171, v0
	v_exp_f32_e32 v155, v16
	v_sub_f32_e32 v16, v173, v0
	s_waitcnt lgkmcnt(2)
	v_mfma_f32_32x32x16_bf16 v[158:173], v[2:5], v[6:9], 0
	v_exp_f32_e32 v14, v14
	v_exp_f32_e32 v154, v16
	s_waitcnt lgkmcnt(0)
	v_mfma_f32_32x32x16_bf16 v[158:173], v[10:13], v[146:149], v[158:173]
	ds_read_b128 v[6:9], v250
	ds_read_b128 v[150:153], v246
	v_sub_f32_e32 v2, v174, v0
	v_exp_f32_e32 v157, v2
	v_sub_f32_e32 v2, v175, v0
	v_exp_f32_e32 v156, v2
	v_sub_f32_e32 v2, v176, v0
	v_exp_f32_e32 v175, v2
	v_sub_f32_e32 v2, v177, v0
	v_exp_f32_e32 v174, v2
	v_cvt_pk_bf16_f32 v2, v15, v14
	v_cvt_pk_bf16_f32 v3, v155, v154
	v_cvt_pk_bf16_f32 v4, v157, v156
	v_cvt_pk_bf16_f32 v5, v175, v174
	s_waitcnt lgkmcnt(0)
	v_mfma_f32_32x32x16_bf16 v[158:173], v[6:9], v[150:153], v[158:173]
	ds_read_b128 v[10:13], v251
	ds_read_b128 v[146:149], v247
	v_sub_f32_e32 v16, v178, v0
	v_exp_f32_e32 v177, v16
	v_sub_f32_e32 v16, v179, v0
	v_exp_f32_e32 v176, v16
	v_sub_f32_e32 v16, v180, v0
	v_exp_f32_e32 v179, v16
	v_sub_f32_e32 v16, v181, v0
	v_exp_f32_e32 v178, v16
	v_sub_f32_e32 v6, v182, v0
	s_waitcnt lgkmcnt(0)
	v_mfma_f32_32x32x16_bf16 v[158:173], v[10:13], v[146:149], v[158:173]
	v_add_f32_e64 v14, v14, 0
	v_add_f32_e64 v15, v15, 0
	v_exp_f32_e32 v7, v6
	v_sub_f32_e32 v6, v183, v0
	v_sub_f32_e32 v8, v184, v0
	v_pk_add_f32 v[14:15], v[154:155], v[14:15]
	v_exp_f32_e32 v6, v6
	v_exp_f32_e32 v9, v8
	v_sub_f32_e32 v8, v185, v0
	v_pk_add_f32 v[14:15], v[156:157], v[14:15]
	v_exp_f32_e32 v8, v8
	v_pk_add_f32 v[14:15], v[174:175], v[14:15]
	v_cvt_pk_bf16_f32 v10, v177, v176
	v_cvt_pk_bf16_f32 v11, v179, v178
	v_cvt_pk_bf16_f32 v12, v7, v6
	v_cvt_pk_bf16_f32 v13, v9, v8
	s_nop 0
	v_pk_add_f32 v[14:15], v[176:177], v[14:15]
	s_nop 0
	v_pk_add_f32 v[14:15], v[178:179], v[14:15]
	s_nop 0
	v_pk_add_f32 v[6:7], v[6:7], v[14:15]
	s_nop 0
	v_pk_add_f32 v[6:7], v[8:9], v[6:7]
	s_nop 0
	v_add_f32_e32 v6, v6, v7
	v_cndmask_b32_e64 v7, 0, 1, s[36:37]
	v_cmp_nge_f32_e32 vcc, s58, v6
	v_cmp_ne_u32_e64 s[4:5], 1, v7
	s_cbranch_vccz .LBB0_305
; #define ATT_LAS __attribute__((address_space(3)))
; __device__ __forceinline__ int sub1(int a) { int v = a ^ 128; asm volatile("" : "+v"(v)); return v; }
; #define ATT_MFMA(a, b, c) __builtin_amdgcn_mfma_f32_32x32x16_bf16((a), (b), (c), 0, 0, 0)
; template <bool C1> __device__ __forceinline__ void qk_issue(f32x16& s0, const ATT_LAS unsigned char* kb, const ATT_LAS unsigned char* qb_, const int (&kaddr)[4]) {
; #pragma unroll
;     for (int i = 0; i < 16; ++i) s0[i] = 0.f;
; #pragma unroll
;     for (int ds = 0; ds < 4; ++ds) {
;         const int ad = C1 ? sub1(kaddr[ds]) : kaddr[ds];
;         const bf16x8 a0 = *(const ATT_LAS bf16x8*)(kb + ad);
;         const bf16x8 qv = *(const ATT_LAS bf16x8*)(qb_ + ad);
;         s0 = ATT_MFMA(a0, qv, s0);
;     }
; }
; __device__ __forceinline__ void rowmax_rescale(bool MASK, f32x16& s0, f32x16 (&O)[4], float& m, float& l, int kvr, int r, int h, ATT_LAS float* wsf) {
;     if (MASK) {
;         asm volatile("" ::: "memory");
;         const int d = r - 4 * h - kvr;
; #pragma unroll
;         for (int i = 0; i < 16; ++i) { if (((i & 3) + 8 * (i >> 2)) > d) s0[i] = -INFINITY; }
.Lslow_1:
	ds_read_b128 v[2:5], v216
	ds_read_b128 v[6:9], v217
	s_and_b64 vcc, exec, s[4:5]
	s_waitcnt lgkmcnt(0)
	v_mfma_f32_32x32x16_bf16 v[174:189], v[2:5], v[6:9], 0
	ds_read_b128 v[2:5], v218
	ds_read_b128 v[6:9], v219
	s_waitcnt lgkmcnt(0)
	v_mfma_f32_32x32x16_bf16 v[174:189], v[2:5], v[6:9], v[174:189]
	ds_read_b128 v[2:5], v220
	ds_read_b128 v[6:9], v221
	s_waitcnt lgkmcnt(0)
	v_mfma_f32_32x32x16_bf16 v[174:189], v[2:5], v[6:9], v[174:189]
	ds_read_b128 v[2:5], v222
	ds_read_b128 v[6:9], v223
	s_waitcnt lgkmcnt(0)
	v_mfma_f32_32x32x16_bf16 v[174:189], v[2:5], v[6:9], v[174:189]
	s_cbranch_vccnz .LBB0_301
	v_cmp_gt_i32_e32 vcc, 27, v214
	s_and_saveexec_b64 s[36:37], vcc
	s_cbranch_execz .LBB0_300
	v_cmp_gt_i32_e32 vcc, 24, v214
	v_cmp_gt_i32_e64 s[34:35], 25, v214
	v_cmp_gt_i32_e64 s[6:7], 19, v214
	s_and_b64 vcc, s[34:35], vcc
	v_cmp_gt_i32_e64 s[8:9], 18, v214
	s_nop 2
	v_cndmask_b32_e32 v3, v186, v17, vcc
	s_and_b64 vcc, vcc, s[6:7]
	v_cmp_gt_i32_e64 s[10:11], 17, v214
	v_cndmask_b32_e32 v4, v185, v17, vcc
	s_and_b64 vcc, vcc, s[8:9]
	v_cmp_gt_i32_e64 s[12:13], 16, v214
	v_cndmask_b32_e32 v5, v184, v17, vcc
	s_and_b64 vcc, vcc, s[10:11]
	v_cmp_gt_i32_e64 s[14:15], 11, v214
	v_cndmask_b32_e32 v6, v183, v17, vcc
	s_and_b64 vcc, vcc, s[12:13]
	v_cmp_gt_i32_e64 s[16:17], 10, v214
	v_cndmask_b32_e32 v7, v182, v17, vcc
	s_and_b64 vcc, vcc, s[14:15]
	v_cmp_gt_i32_e64 s[18:19], 9, v214
	v_cndmask_b32_e32 v8, v181, v17, vcc
	s_and_b64 vcc, vcc, s[16:17]
	v_cmp_gt_i32_e64 s[20:21], 8, v214
	v_cndmask_b32_e32 v16, v180, v17, vcc
	s_and_b64 vcc, vcc, s[18:19]
	v_cmp_gt_i32_e64 s[22:23], 3, v214
	v_cndmask_b32_e32 v146, v179, v17, vcc
	s_and_b64 vcc, vcc, s[20:21]
	v_cmp_gt_i32_e64 s[24:25], 2, v214
	v_cndmask_b32_e32 v147, v178, v17, vcc
	s_and_b64 vcc, vcc, s[22:23]
	v_cmp_gt_i32_e64 s[26:27], 1, v214
	v_cndmask_b32_e32 v148, v177, v17, vcc
	s_and_b64 vcc, vcc, s[24:25]
	v_cmp_gt_i32_e64 s[28:29], 0, v214
	v_cndmask_b32_e32 v149, v176, v17, vcc
	s_and_b64 vcc, vcc, s[26:27]
	v_cndmask_b32_e32 v150, v175, v17, vcc
	s_and_b64 vcc, vcc, s[28:29]
	v_cndmask_b32_e32 v151, v174, v17, vcc
	v_cmp_eq_u32_e32 vcc, 26, v214
	v_cndmask_b32_e64 v2, v187, v17, s[34:35]
	s_nop 0
	v_cndmask_b32_e32 v9, v8, v181, vcc
	v_cndmask_b32_e32 v8, v16, v180, vcc
	v_cndmask_b32_e32 v16, v17, v188, vcc
	v_cndmask_b32_e32 v15, v2, v187, vcc
	v_cndmask_b32_e32 v14, v3, v186, vcc
	v_cndmask_b32_e32 v13, v4, v185, vcc
	v_cndmask_b32_e32 v12, v5, v184, vcc
	v_cndmask_b32_e32 v11, v6, v183, vcc
	v_cndmask_b32_e32 v10, v7, v182, vcc
	v_cndmask_b32_e32 v7, v146, v179, vcc
	v_cndmask_b32_e32 v6, v147, v178, vcc
	v_cndmask_b32_e32 v5, v148, v177, vcc
	v_cndmask_b32_e32 v4, v149, v176, vcc
	v_cndmask_b32_e32 v3, v150, v175, vcc
	v_cndmask_b32_e32 v2, v151, v174, vcc
	v_mov_b64_e32 v[188:189], v[16:17]
	v_mov_b64_e32 v[186:187], v[14:15]
	v_mov_b64_e32 v[184:185], v[12:13]
	v_mov_b64_e32 v[182:183], v[10:11]
	v_mov_b64_e32 v[180:181], v[8:9]
	v_mov_b64_e32 v[178:179], v[6:7]
	v_mov_b64_e32 v[176:177], v[4:5]
	v_mov_b64_e32 v[174:175], v[2:3]

; __device__ __forceinline__ float half_max(float v) { auto rr = __builtin_amdgcn_permlane32_swap(__float_as_uint(v), __float_as_uint(v), false, false); return fmaxf(__uint_as_float(rr[0]), __uint_as_float(rr[1])); }
; __device__ __forceinline__ int crow(int r, int hi) { return (r & 3) + 8 * (r >> 2) + 4 * hi; }
; __device__ __forceinline__ void rowmax_rescale(bool MASK, f32x16& s0, f32x16 (&O)[4], float& m, float& l, int kvr, int r, int h, ATT_LAS float* wsf) {
;     ...
;     float ra = __builtin_fmaxf(__builtin_fmaxf(s0[0], s0[1]), s0[2]), rb = __builtin_fmaxf(__builtin_fmaxf(s0[3], s0[4]), s0[5]);
;     ra = __builtin_fmaxf(__builtin_fmaxf(ra, s0[6]), s0[7]); rb = __builtin_fmaxf(__builtin_fmaxf(rb, s0[8]), s0[9]);
;     ra = __builtin_fmaxf(__builtin_fmaxf(ra, s0[10]), s0[11]); rb = __builtin_fmaxf(__builtin_fmaxf(rb, s0[12]), s0[13]);
;     ra = __builtin_fmaxf(__builtin_fmaxf(ra, s0[14]), s0[15]);
;     const float rm = half_max(__builtin_fmaxf(ra, rb));
;     if (__any(rm > m + THR)) {
;         const float mn = fmaxf(m, rm), al = __builtin_amdgcn_exp2f(m - mn);
;         l *= al; m = mn;
;         if (h == 0) wsf[r] = al;
; #pragma unroll
;         for (int i = 0; i < 16; ++i) { const float a = wsf[crow(i, h)];
; #pragma unroll
;             for (int db = 0; db < 4; ++db) O[db][i] *= a; }
.LBB0_301:
	s_nop 6
	v_max_f32_e32 v2, v175, v175
	v_max_f32_e32 v3, v174, v174
	v_max_f32_e32 v2, v3, v2
	v_max3_f32 v3, v177, v178, v179
	v_max3_f32 v2, v2, v176, v180
	v_max3_f32 v3, v3, v182, v183
	v_max3_f32 v2, v2, v181, v184
	v_max3_f32 v3, v3, v186, v187
	v_max3_f32 v2, v2, v185, v188
	v_max3_f32 v2, v2, v189, v3
	v_mov_b32_e32 v3, v2
	s_nop 1
	v_permlane32_swap_b32_e32 v2, v3
	v_max_f32_e32 v3, v3, v3
	v_max_f32_e32 v2, v2, v2
	v_max_f32_e32 v2, v2, v3
	v_add_f32_e32 v3, 0x41000000, v0
	v_cmp_gt_f32_e32 vcc, v2, v3
	s_cbranch_vccz .LBB0_306
	v_max_f32_e32 v2, v2, v2
	v_max_f32_e32 v3, v0, v0
	v_max_f32_e32 v6, v3, v2
	v_cmp_gt_f32_e32 vcc, 0xf0000000, v3
	s_nop 1
	v_cndmask_b32_e64 v253, v6, 0, vcc
	v_cmp_gt_f32_e64 vcc, s100, |v2|
	s_nop 1
	v_cndmask_b32_e32 v6, v6, v253, vcc
	v_sub_f32_e32 v0, v0, v6
	v_exp_f32_e32 v0, v0
	s_and_saveexec_b64 s[6:7], s[2:3]
	ds_write_b32 v202, v0
	s_or_b64 exec, exec, s[6:7]
	v_add_u32_e32 v7, s78, v208
	ds_read_b128 v[2:5], v7 offset:96
	ds_read_b128 v[8:11], v7 offset:64
	ds_read_b128 v[12:15], v7 offset:32
	ds_read_b128 v[146:149], v7
	v_mul_f32_e32 v225, v225, v0
	s_waitcnt lgkmcnt(3)
	v_pk_mul_f32 v[46:47], v[46:47], v[2:3]
	s_waitcnt lgkmcnt(2)
	v_pk_mul_f32 v[42:43], v[42:43], v[8:9]
	s_waitcnt lgkmcnt(1)
	v_pk_mul_f32 v[38:39], v[38:39], v[12:13]
	v_pk_mul_f32 v[48:49], v[48:49], v[4:5]
	v_pk_mul_f32 v[44:45], v[44:45], v[10:11]
	v_pk_mul_f32 v[40:41], v[40:41], v[14:15]
	s_waitcnt lgkmcnt(0)
	v_pk_mul_f32 v[36:37], v[36:37], v[148:149]
	v_pk_mul_f32 v[34:35], v[34:35], v[146:147]
	v_pk_mul_f32 v[62:63], v[62:63], v[2:3]
	v_pk_mul_f32 v[58:59], v[58:59], v[8:9]
	v_pk_mul_f32 v[54:55], v[54:55], v[12:13]
	v_pk_mul_f32 v[64:65], v[64:65], v[4:5]
	v_pk_mul_f32 v[60:61], v[60:61], v[10:11]
	v_pk_mul_f32 v[56:57], v[56:57], v[14:15]
	v_pk_mul_f32 v[52:53], v[52:53], v[148:149]
	v_pk_mul_f32 v[50:51], v[50:51], v[146:147]
	v_pk_mul_f32 v[78:79], v[78:79], v[2:3]
	v_pk_mul_f32 v[74:75], v[74:75], v[8:9]
	v_pk_mul_f32 v[70:71], v[70:71], v[12:13]
	v_pk_mul_f32 v[80:81], v[80:81], v[4:5]
	v_pk_mul_f32 v[76:77], v[76:77], v[10:11]
	v_pk_mul_f32 v[72:73], v[72:73], v[14:15]
	v_pk_mul_f32 v[68:69], v[68:69], v[148:149]
	v_pk_mul_f32 v[66:67], v[66:67], v[146:147]
	v_pk_mul_f32 v[94:95], v[94:95], v[2:3]
	v_pk_mul_f32 v[90:91], v[90:91], v[8:9]
	v_pk_mul_f32 v[86:87], v[86:87], v[12:13]
	v_pk_mul_f32 v[96:97], v[96:97], v[4:5]
	v_pk_mul_f32 v[92:93], v[92:93], v[10:11]
	v_pk_mul_f32 v[88:89], v[88:89], v[14:15]
	v_pk_mul_f32 v[84:85], v[84:85], v[148:149]
	v_pk_mul_f32 v[82:83], v[82:83], v[146:147]
	s_branch .LBB0_307

; #define ATT_LAS __attribute__((address_space(3)))
; __device__ __forceinline__ int sub1(int a) { int v = a ^ 128; asm volatile("" : "+v"(v)); return v; }
; #define ATT_MFMA(a, b, c) __builtin_amdgcn_mfma_f32_32x32x16_bf16((a), (b), (c), 0, 0, 0)
; template <bool C1> __device__ __forceinline__ void qk_issue(f32x16& s0, const ATT_LAS unsigned char* kb, const ATT_LAS unsigned char* qb_, const int (&kaddr)[4]) {
; #pragma unroll
;     for (int i = 0; i < 16; ++i) s0[i] = 0.f;
; #pragma unroll
;     for (int ds = 0; ds < 4; ++ds) {
;         const int ad = C1 ? sub1(kaddr[ds]) : kaddr[ds];
;         const bf16x8 a0 = *(const ATT_LAS bf16x8*)(kb + ad);
;         const bf16x8 qv = *(const ATT_LAS bf16x8*)(qb_ + ad);
;         s0 = ATT_MFMA(a0, qv, s0);
;     }
; }
; __device__ __forceinline__ void rowmax_rescale(bool MASK, f32x16& s0, f32x16 (&O)[4], float& m, float& l, int kvr, int r, int h, ATT_LAS float* wsf) {
;     if (MASK) {
;         asm volatile("" ::: "memory");
;         const int d = r - 4 * h - kvr;
; #pragma unroll
;         for (int i = 0; i < 16; ++i) { if (((i & 3) + 8 * (i >> 2)) > d) s0[i] = -INFINITY; }
; template <bool C1> __device__ __forceinline__ void slow_step(bool MASK, f32x16& S, const ATT_LAS unsigned char* kb, const ATT_LAS unsigned char* qbase, const int (&kaddr)[4], const int (&vaddr)[2], ...
;     l = l_saved;
;     qk_issue<C1>(S, kb, qbase, kaddr);
;     rowmax_rescale(MASK, S, O, m, l, kvr, r, h, wsf);
;     f32x16 dummy;
;     step_fused<false, false, false>(S, m, l, pk, O, pk, kb, vaddr, dummy, kb, qbase, kaddr);
; }
.Lslow_2:
	v_mov_b32_e32 v6, v209
	v_mov_b32_e32 v10, v210
	v_add_u32_e32 v2, s81, v6
	ds_read_b128 v[2:5], v2
	v_add_u32_e32 v6, s51, v6
	ds_read_b128 v[6:9], v6
	s_and_b64 vcc, exec, s[4:5]
	v_add_u32_e32 v11, s81, v10
	s_waitcnt lgkmcnt(0)
	v_mfma_f32_32x32x16_bf16 v[162:177], v[2:5], v[6:9], 0
	ds_read_b128 v[2:5], v11
	v_add_u32_e32 v6, s51, v10
	ds_read_b128 v[6:9], v6
	v_mov_b32_e32 v10, v211
	s_nop 0
	v_add_u32_e32 v11, s81, v10
	s_waitcnt lgkmcnt(0)
	v_mfma_f32_32x32x16_bf16 v[162:177], v[2:5], v[6:9], v[162:177]
	ds_read_b128 v[2:5], v11
	v_add_u32_e32 v6, s51, v10
	ds_read_b128 v[6:9], v6
	v_mov_b32_e32 v10, v212
	s_nop 0
	v_add_u32_e32 v11, s81, v10
	s_waitcnt lgkmcnt(0)
	v_mfma_f32_32x32x16_bf16 v[162:177], v[2:5], v[6:9], v[162:177]
	ds_read_b128 v[2:5], v11
	v_add_u32_e32 v6, s51, v10
	ds_read_b128 v[6:9], v6
	s_waitcnt lgkmcnt(0)
	v_mfma_f32_32x32x16_bf16 v[162:177], v[2:5], v[6:9], v[162:177]
	s_cbranch_vccnz .LBB0_316
	v_cmp_gt_i32_e32 vcc, 27, v214
	s_and_saveexec_b64 s[36:37], vcc
	s_cbranch_execz .LBB0_315
	v_cmp_gt_i32_e32 vcc, 24, v214
	v_cmp_gt_i32_e64 s[34:35], 25, v214
	v_cmp_gt_i32_e64 s[6:7], 19, v214
	s_and_b64 vcc, s[34:35], vcc
	v_cmp_gt_i32_e64 s[8:9], 18, v214
	s_nop 2
	v_cndmask_b32_e32 v3, v174, v17, vcc
	s_and_b64 vcc, vcc, s[6:7]
	v_cmp_gt_i32_e64 s[10:11], 17, v214
	v_cndmask_b32_e32 v4, v173, v17, vcc
	s_and_b64 vcc, vcc, s[8:9]
	v_cmp_gt_i32_e64 s[12:13], 16, v214
	v_cndmask_b32_e32 v5, v172, v17, vcc
	s_and_b64 vcc, vcc, s[10:11]
	v_cmp_gt_i32_e64 s[14:15], 11, v214
	v_cndmask_b32_e32 v6, v171, v17, vcc
	s_and_b64 vcc, vcc, s[12:13]
	v_cmp_gt_i32_e64 s[16:17], 10, v214
	v_cndmask_b32_e32 v7, v170, v17, vcc
	s_and_b64 vcc, vcc, s[14:15]
	v_cmp_gt_i32_e64 s[18:19], 9, v214
	v_cndmask_b32_e32 v8, v169, v17, vcc
	s_and_b64 vcc, vcc, s[16:17]
	v_cmp_gt_i32_e64 s[20:21], 8, v214
	v_cndmask_b32_e32 v16, v168, v17, vcc
	s_and_b64 vcc, vcc, s[18:19]
	v_cmp_gt_i32_e64 s[22:23], 3, v214
	v_cndmask_b32_e32 v177, v167, v17, vcc
	s_and_b64 vcc, vcc, s[20:21]
	v_cmp_gt_i32_e64 s[24:25], 2, v214
	v_cndmask_b32_e32 v181, v166, v17, vcc
	s_and_b64 vcc, vcc, s[22:23]
	v_cmp_gt_i32_e64 s[26:27], 1, v214
	v_cndmask_b32_e32 v182, v165, v17, vcc
	s_and_b64 vcc, vcc, s[24:25]
	v_cmp_gt_i32_e64 s[28:29], 0, v214
	v_cndmask_b32_e32 v183, v164, v17, vcc
	s_and_b64 vcc, vcc, s[26:27]
	v_cndmask_b32_e32 v184, v163, v17, vcc
	s_and_b64 vcc, vcc, s[28:29]
	v_cndmask_b32_e32 v185, v162, v17, vcc
	v_cmp_eq_u32_e32 vcc, 26, v214
	v_cndmask_b32_e64 v2, v175, v17, s[34:35]
	s_nop 0
	v_cndmask_b32_e32 v9, v8, v169, vcc
	v_cndmask_b32_e32 v8, v16, v168, vcc
	v_cndmask_b32_e32 v16, v17, v176, vcc
	v_cndmask_b32_e32 v15, v2, v175, vcc
	v_cndmask_b32_e32 v14, v3, v174, vcc
	v_cndmask_b32_e32 v13, v4, v173, vcc
	v_cndmask_b32_e32 v12, v5, v172, vcc
	v_cndmask_b32_e32 v11, v6, v171, vcc
	v_cndmask_b32_e32 v10, v7, v170, vcc
	v_cndmask_b32_e32 v7, v177, v167, vcc
	v_cndmask_b32_e32 v6, v181, v166, vcc
	v_cndmask_b32_e32 v5, v182, v165, vcc
	v_cndmask_b32_e32 v4, v183, v164, vcc
	v_cndmask_b32_e32 v3, v184, v163, vcc
	v_cndmask_b32_e32 v2, v185, v162, vcc
	v_mov_b64_e32 v[176:177], v[16:17]
	v_mov_b64_e32 v[174:175], v[14:15]
	v_mov_b64_e32 v[172:173], v[12:13]
	v_mov_b64_e32 v[170:171], v[10:11]
	v_mov_b64_e32 v[168:169], v[8:9]
	v_mov_b64_e32 v[166:167], v[6:7]
	v_mov_b64_e32 v[164:165], v[4:5]
	v_mov_b64_e32 v[162:163], v[2:3]

; __device__ __forceinline__ float half_max(float v) { auto rr = __builtin_amdgcn_permlane32_swap(__float_as_uint(v), __float_as_uint(v), false, false); return fmaxf(__uint_as_float(rr[0]), __uint_as_float(rr[1])); }
; __device__ __forceinline__ int crow(int r, int hi) { return (r & 3) + 8 * (r >> 2) + 4 * hi; }
; __device__ __forceinline__ void rowmax_rescale(bool MASK, f32x16& s0, f32x16 (&O)[4], float& m, float& l, int kvr, int r, int h, ATT_LAS float* wsf) {
;     ...
;     float ra = __builtin_fmaxf(__builtin_fmaxf(s0[0], s0[1]), s0[2]), rb = __builtin_fmaxf(__builtin_fmaxf(s0[3], s0[4]), s0[5]);
;     ra = __builtin_fmaxf(__builtin_fmaxf(ra, s0[6]), s0[7]); rb = __builtin_fmaxf(__builtin_fmaxf(rb, s0[8]), s0[9]);
;     ra = __builtin_fmaxf(__builtin_fmaxf(ra, s0[10]), s0[11]); rb = __builtin_fmaxf(__builtin_fmaxf(rb, s0[12]), s0[13]);
;     ra = __builtin_fmaxf(__builtin_fmaxf(ra, s0[14]), s0[15]);
;     const float rm = half_max(__builtin_fmaxf(ra, rb));
;     if (__any(rm > m + THR)) {
;         const float mn = fmaxf(m, rm), al = __builtin_amdgcn_exp2f(m - mn);
;         l *= al; m = mn;
;         if (h == 0) wsf[r] = al;
; #pragma unroll
;         for (int i = 0; i < 16; ++i) { const float a = wsf[crow(i, h)];
; #pragma unroll
;             for (int db = 0; db < 4; ++db) O[db][i] *= a; }
.LBB0_316:
	s_nop 6
	v_max_f32_e32 v2, v163, v163
	v_max_f32_e32 v3, v162, v162
	v_max_f32_e32 v2, v3, v2
	v_max3_f32 v3, v165, v166, v167
	v_max3_f32 v2, v2, v164, v168
	v_max3_f32 v3, v3, v170, v171
	v_max3_f32 v2, v2, v169, v172
	v_max3_f32 v3, v3, v174, v175
	v_max3_f32 v2, v2, v173, v176
	v_max3_f32 v2, v2, v177, v3
	v_mov_b32_e32 v3, v2
	s_nop 1
	v_permlane32_swap_b32_e32 v2, v3
	v_max_f32_e32 v3, v3, v3
	v_max_f32_e32 v2, v2, v2
	v_max_f32_e32 v2, v2, v3
	v_add_f32_e32 v3, 0x41000000, v215
	v_cmp_gt_f32_e32 vcc, v2, v3
	s_cbranch_vccz .LBB0_321
	v_max_f32_e32 v2, v2, v2
	v_max_f32_e32 v3, v215, v215
	v_max_f32_e32 v10, v3, v2
	v_cmp_gt_f32_e32 vcc, 0xf0000000, v3
	s_nop 1
	v_cndmask_b32_e64 v253, v10, 0, vcc
	v_cmp_gt_f32_e64 vcc, s100, |v2|
	s_nop 1
	v_cndmask_b32_e32 v10, v10, v253, vcc
	v_sub_f32_e32 v2, v215, v10
	v_exp_f32_e32 v2, v2
	s_and_saveexec_b64 s[6:7], s[2:3]
	ds_write_b32 v202, v2
	s_or_b64 exec, exec, s[6:7]
	v_add_u32_e32 v3, s78, v208
	ds_read_b128 v[4:7], v3 offset:96
	ds_read_b128 v[12:15], v3 offset:64
	ds_read_b128 v[182:185], v3 offset:32
	ds_read_b128 v[186:189], v3
	v_mul_f32_e32 v224, v224, v2
	s_waitcnt lgkmcnt(3)
	v_pk_mul_f32 v[142:143], v[142:143], v[4:5]
	s_waitcnt lgkmcnt(2)
	v_pk_mul_f32 v[138:139], v[138:139], v[12:13]
	s_waitcnt lgkmcnt(1)
	v_pk_mul_f32 v[134:135], v[134:135], v[182:183]
	v_pk_mul_f32 v[144:145], v[144:145], v[6:7]
	v_pk_mul_f32 v[140:141], v[140:141], v[14:15]
	v_pk_mul_f32 v[136:137], v[136:137], v[184:185]
	s_waitcnt lgkmcnt(0)
	v_pk_mul_f32 v[132:133], v[132:133], v[188:189]
	v_pk_mul_f32 v[130:131], v[130:131], v[186:187]
	v_pk_mul_f32 v[126:127], v[126:127], v[4:5]
	v_pk_mul_f32 v[122:123], v[122:123], v[12:13]
	v_pk_mul_f32 v[118:119], v[118:119], v[182:183]
	v_pk_mul_f32 v[128:129], v[128:129], v[6:7]
	v_pk_mul_f32 v[124:125], v[124:125], v[14:15]
	v_pk_mul_f32 v[120:121], v[120:121], v[184:185]
	v_pk_mul_f32 v[116:117], v[116:117], v[188:189]
	v_pk_mul_f32 v[114:115], v[114:115], v[186:187]
	v_pk_mul_f32 v[110:111], v[110:111], v[4:5]
	v_pk_mul_f32 v[106:107], v[106:107], v[12:13]
	v_pk_mul_f32 v[102:103], v[102:103], v[182:183]
	v_pk_mul_f32 v[112:113], v[112:113], v[6:7]
	v_pk_mul_f32 v[108:109], v[108:109], v[14:15]
	v_pk_mul_f32 v[104:105], v[104:105], v[184:185]
	v_pk_mul_f32 v[100:101], v[100:101], v[188:189]
	v_pk_mul_f32 v[98:99], v[98:99], v[186:187]
	v_pk_mul_f32 v[30:31], v[30:31], v[4:5]
	v_pk_mul_f32 v[26:27], v[26:27], v[12:13]
	v_pk_mul_f32 v[22:23], v[22:23], v[182:183]
	v_pk_mul_f32 v[32:33], v[32:33], v[6:7]
	v_pk_mul_f32 v[28:29], v[28:29], v[14:15]
	v_pk_mul_f32 v[24:25], v[24:25], v[184:185]
	v_pk_mul_f32 v[20:21], v[20:21], v[188:189]
	v_pk_mul_f32 v[18:19], v[18:19], v[186:187]
	s_branch .LBB0_322

; template <bool HAS_PV, bool HAS_QK, bool C1> ...
;     s16x4 vlo[2], vhi[2]; bf16x8 ka, qa;
;     if (HAS_PV) {
; #pragma unroll
;         for (int u = 0; u < 2; ++u) { vlo[u] = vtr(vb + vaddr[0] + u * 512); vhi[u] = vtr(vb + vaddr[1] + u * 512); } }
;     if (HAS_QK) { const int ad = C1 ? sub1(kaddr[0]) : kaddr[0]; ka = *(const ATT_LAS bf16x8*)(kb + ad); qa = *(const ATT_LAS bf16x8*)(qb_ + ad);
; #pragma unroll
;         for (int i = 0; i < 16; ++i) Snext[i] = 0.f; }
;     float sa = 0.f, sb = 0.f;
; #pragma unroll
;     for (int g = 0; g < 4; ++g) {
;         s16x4 nlo[2], nhi[2]; bf16x8 nk, nq;
;         if (g < 3) {
;             if (HAS_PV) {
; #pragma unroll
;                 for (int u = 0; u < 2; ++u) { const int off = (2 * ((g + 1) & 1) + u) * 512 + ((g + 1) >> 1) * 4096; nlo[u] = vtr(vb + vaddr[0] + off); nhi[u] = vtr(vb + vaddr[1] + off); } }
;             if (HAS_QK) { const int ad = C1 ? sub1(kaddr[g + 1]) : kaddr[g + 1]; nk = *(const ATT_LAS bf16x8*)(kb + ad); nq = *(const ATT_LAS bf16x8*)(qb_ + ad); }
;         }
;         if (HAS_PV) { const bf16x8 pa = __builtin_bit_cast(bf16x8, pkin[g >> 1]);
; #pragma unroll
;             for (int u = 0; u < 2; ++u) { const bf16x8 vf = __builtin_shufflevector(vlo[u], vhi[u], 0, 1, 2, 3, 4, 5, 6, 7); Opv[2 * (g & 1) + u] = ATT_MFMA(pa, vf, Opv[2 * (g & 1) + u]); } }
;         if (HAS_QK) Snext = ATT_MFMA(ka, qa, Snext);
; #pragma unroll
;         for (int e = 4 * g; e < 4 * g + 4; e += 2) { Scur[e] = __builtin_amdgcn_exp2f(Scur[e] - m); Scur[e + 1] = __builtin_amdgcn_exp2f(Scur[e + 1] - m); sa += Scur[e]; sb += Scur[e + 1]; }
;         if (g & 1) pkout[g >> 1] = (u32x4){cvtpk(Scur[4 * g - 4], Scur[4 * g - 3]), cvtpk(Scur[4 * g - 2], Scur[4 * g - 1]), cvtpk(Scur[4 * g], Scur[4 * g + 1]), cvtpk(Scur[4 * g + 2], Scur[4 * g + 3])};
;         if (g < 3) {
;             if (HAS_PV) {
; #pragma unroll
;                 for (int u = 0; u < 2; ++u) { vlo[u] = nlo[u]; vhi[u] = nhi[u]; } }
;             if (HAS_QK) { ka = nk; qa = nq; }
;         }
;         __builtin_amdgcn_sched_barrier(0);
;     }
;     l += sa + sb;
;     return sa + sb;
; }
; __device__ __forceinline__ void tile_body(bool MASK, const ATT_LAS unsigned char* kb, const ATT_LAS unsigned char* vb, const ATT_LAS unsigned char* qbase, const int (&kaddr)[4], const int (&vaddr)[2], ...
;     ...
;     apply_mask(MASK, Sa, kvrel + 32, r, h); ls = l1;
.LBB0_326:
	ds_read_b64_tr_b16 v[10:11], v179 offset:32768
	ds_read_b64_tr_b16 v[12:13], v178 offset:34816
	ds_read_b64_tr_b16 v[164:165], v178 offset:35328
	ds_read_b64_tr_b16 v[162:163], v179 offset:33280
	s_waitcnt lgkmcnt(2)
	v_mfma_f32_32x32x16_bf16 v[130:145], v[2:5], v[10:13], v[130:145]
	ds_read_b128 v[166:169], v248 offset:8192
	ds_read_b128 v[170:173], v244
	ds_read_b64_tr_b16 v[10:11], v179 offset:33792
	ds_read_b64_tr_b16 v[12:13], v178 offset:35840
	ds_read_b64_tr_b16 v[184:185], v178 offset:36352
	ds_read_b64_tr_b16 v[182:183], v179 offset:34304
	v_sub_f32_e32 v16, v148, v0
	s_waitcnt lgkmcnt(6)
	v_mfma_f32_32x32x16_bf16 v[114:129], v[2:5], v[162:165], v[114:129]
	ds_read_b128 v[186:189], v249 offset:8192
	ds_read_b128 v[224:227], v245
	v_sub_f32_e32 v14, v146, v0
	v_exp_f32_e32 v15, v14
	v_sub_f32_e32 v14, v147, v0
	v_exp_f32_e32 v237, v16
	s_waitcnt lgkmcnt(6)
	v_mfma_f32_32x32x16_bf16 v[162:177], v[166:169], v[170:173], 0
	v_sub_f32_e32 v16, v149, v0
	v_exp_f32_e32 v14, v14
	v_exp_f32_e32 v236, v16
	s_waitcnt lgkmcnt(4)
	v_mfma_f32_32x32x16_bf16 v[98:113], v[2:5], v[10:13], v[98:113]
	ds_read_b64_tr_b16 v[146:147], v179 offset:36864
	ds_read_b64_tr_b16 v[148:149], v178 offset:38912
	ds_read_b64_tr_b16 v[230:231], v178 offset:39424
	ds_read_b64_tr_b16 v[228:229], v179 offset:37376
	ds_read_b128 v[10:13], v250 offset:8192
	ds_read_b128 v[232:235], v246
	s_waitcnt lgkmcnt(8)
	v_mfma_f32_32x32x16_bf16 v[18:33], v[2:5], v[182:185], v[18:33]
	v_sub_f32_e32 v16, v150, v0
	v_sub_f32_e32 v2, v152, v0
	v_exp_f32_e32 v239, v16
	v_sub_f32_e32 v16, v151, v0
	v_exp_f32_e32 v241, v2
	v_sub_f32_e32 v2, v153, v0
	v_exp_f32_e32 v238, v16
	s_waitcnt lgkmcnt(6)
	v_mfma_f32_32x32x16_bf16 v[162:177], v[186:189], v[224:227], v[162:177]
	v_exp_f32_e32 v240, v2
	v_cvt_pk_bf16_f32 v2, v15, v14
	v_cvt_pk_bf16_f32 v3, v237, v236
	v_cvt_pk_bf16_f32 v4, v239, v238
	v_cvt_pk_bf16_f32 v5, v241, v240
	s_waitcnt lgkmcnt(4)
	v_mfma_f32_32x32x16_bf16 v[130:145], v[6:9], v[146:149], v[130:145]
	ds_read_b64_tr_b16 v[146:147], v179 offset:37888
	ds_read_b64_tr_b16 v[148:149], v178 offset:39936
	ds_read_b64_tr_b16 v[152:153], v178 offset:40448
	ds_read_b64_tr_b16 v[150:151], v179 offset:38400
	ds_read_b128 v[182:185], v251 offset:8192
	ds_read_b128 v[186:189], v247
	s_waitcnt lgkmcnt(8)
	v_mfma_f32_32x32x16_bf16 v[114:129], v[6:9], v[228:231], v[114:129]
	v_sub_f32_e32 v16, v154, v0
	v_exp_f32_e32 v225, v16
	v_sub_f32_e32 v16, v155, v0
	v_exp_f32_e32 v224, v16
	v_sub_f32_e32 v16, v156, v0
	v_exp_f32_e32 v155, v16
	v_sub_f32_e32 v16, v157, v0
	s_waitcnt lgkmcnt(6)
	v_mfma_f32_32x32x16_bf16 v[162:177], v[10:13], v[232:235], v[162:177]
	v_exp_f32_e32 v154, v16
	v_sub_f32_e32 v10, v158, v0
	v_exp_f32_e32 v157, v10
	v_sub_f32_e32 v10, v159, v0
	s_waitcnt lgkmcnt(4)
	v_mfma_f32_32x32x16_bf16 v[98:113], v[6:9], v[146:149], v[98:113]
	v_exp_f32_e32 v156, v10
	v_sub_f32_e32 v10, v160, v0
	v_exp_f32_e32 v147, v10
	v_sub_f32_e32 v10, v161, v0
	v_exp_f32_e32 v146, v10
	v_cvt_pk_bf16_f32 v10, v225, v224
	v_cvt_pk_bf16_f32 v11, v155, v154
	s_waitcnt lgkmcnt(2)
	v_mfma_f32_32x32x16_bf16 v[18:33], v[6:9], v[150:153], v[18:33]
	v_add_f32_e64 v6, v14, 0
	v_add_f32_e64 v7, v15, 0
	v_cvt_pk_bf16_f32 v12, v157, v156
	v_cvt_pk_bf16_f32 v13, v147, v146
	v_add_f32_e64 v6, v236, v6
	v_add_f32_e64 v7, v237, v7
	v_add_f32_e64 v6, v238, v6
	v_add_f32_e64 v7, v239, v7
	s_waitcnt lgkmcnt(0)
	v_mfma_f32_32x32x16_bf16 v[162:177], v[182:185], v[186:189], v[162:177]
	v_add_f32_e64 v6, v240, v6
	v_add_f32_e64 v7, v241, v7
	v_add_f32_e64 v6, v224, v6
	v_add_f32_e64 v7, v225, v7
	v_add_f32_e64 v6, v154, v6
	v_add_f32_e64 v7, v155, v7
	v_pk_add_f32 v[6:7], v[156:157], v[6:7]
	s_nop 0
	v_pk_add_f32 v[6:7], v[146:147], v[6:7]
	s_nop 0
	v_add_f32_e32 v6, v6, v7
	v_cmp_nge_f32_e32 vcc, s58, v6
	s_cbranch_vccz .LBB0_335
.Lslow_3:
	ds_read_b128 v[2:5], v216 offset:8192
	ds_read_b128 v[6:9], v217
	s_and_b64 vcc, exec, s[4:5]
	s_waitcnt lgkmcnt(0)
	v_mfma_f32_32x32x16_bf16 v[146:161], v[2:5], v[6:9], 0
	ds_read_b128 v[2:5], v218 offset:8192
	ds_read_b128 v[6:9], v219
	s_waitcnt lgkmcnt(0)
	v_mfma_f32_32x32x16_bf16 v[146:161], v[2:5], v[6:9], v[146:161]
	ds_read_b128 v[2:5], v220 offset:8192
	ds_read_b128 v[6:9], v221
	s_waitcnt lgkmcnt(0)
	v_mfma_f32_32x32x16_bf16 v[146:161], v[2:5], v[6:9], v[146:161]
	ds_read_b128 v[2:5], v222 offset:8192
	ds_read_b128 v[6:9], v223
	s_waitcnt lgkmcnt(0)
	v_mfma_f32_32x32x16_bf16 v[146:161], v[2:5], v[6:9], v[146:161]
	s_cbranch_vccnz .LBB0_331
	v_subrev_u32_e32 v2, 32, v214
	v_cmp_gt_i32_e32 vcc, 27, v2
	s_and_saveexec_b64 s[36:37], vcc
	s_cbranch_execz .LBB0_330
	v_cmp_gt_i32_e32 vcc, 24, v2
	v_cmp_gt_i32_e64 s[34:35], 25, v2
	v_cmp_gt_i32_e64 s[6:7], 19, v2
	s_and_b64 vcc, s[34:35], vcc
	v_cmp_gt_i32_e64 s[8:9], 18, v2
	s_nop 1
	v_cndmask_b32_e32 v3, v158, v17, vcc
	s_and_b64 vcc, vcc, s[6:7]
	v_cmp_gt_i32_e64 s[10:11], 17, v2
	v_cndmask_b32_e32 v4, v157, v17, vcc
	s_and_b64 vcc, vcc, s[8:9]
	v_cmp_gt_i32_e64 s[12:13], 16, v2
	v_cndmask_b32_e32 v5, v156, v17, vcc
	s_and_b64 vcc, vcc, s[10:11]
	v_cmp_gt_i32_e64 s[14:15], 11, v2
	v_cndmask_b32_e32 v6, v155, v17, vcc
	s_and_b64 vcc, vcc, s[12:13]
	v_cmp_gt_i32_e64 s[16:17], 10, v2
	v_cndmask_b32_e32 v7, v154, v17, vcc
	s_and_b64 vcc, vcc, s[14:15]
	v_cmp_gt_i32_e64 s[18:19], 9, v2
	v_cndmask_b32_e32 v8, v153, v17, vcc
	s_and_b64 vcc, vcc, s[16:17]
	v_cmp_gt_i32_e64 s[20:21], 8, v2
	v_cndmask_b32_e32 v16, v152, v17, vcc
	s_and_b64 vcc, vcc, s[18:19]
	v_cmp_gt_i32_e64 s[22:23], 3, v2
	v_cndmask_b32_e32 v161, v151, v17, vcc
	s_and_b64 vcc, vcc, s[20:21]
	v_cmp_gt_i32_e64 s[24:25], 2, v2
	v_cndmask_b32_e32 v182, v150, v17, vcc
	s_and_b64 vcc, vcc, s[22:23]
	v_cmp_gt_i32_e64 s[26:27], 1, v2
	v_cndmask_b32_e32 v183, v149, v17, vcc
	s_and_b64 vcc, vcc, s[24:25]
	v_cmp_gt_i32_e64 s[28:29], 0, v2
	v_cndmask_b32_e32 v184, v148, v17, vcc
	s_and_b64 vcc, vcc, s[26:27]
	v_cndmask_b32_e32 v185, v147, v17, vcc
	s_and_b64 vcc, vcc, s[28:29]
	v_cndmask_b32_e32 v186, v146, v17, vcc
	v_cmp_eq_u32_e32 vcc, 58, v214
	v_cndmask_b32_e64 v2, v159, v17, s[34:35]
	s_nop 0
	v_cndmask_b32_e32 v9, v8, v153, vcc
	v_cndmask_b32_e32 v8, v16, v152, vcc
	v_cndmask_b32_e32 v16, v17, v160, vcc
	v_cndmask_b32_e32 v15, v2, v159, vcc
	v_cndmask_b32_e32 v14, v3, v158, vcc
	v_cndmask_b32_e32 v13, v4, v157, vcc
	v_cndmask_b32_e32 v12, v5, v156, vcc
	v_cndmask_b32_e32 v11, v6, v155, vcc
	v_cndmask_b32_e32 v10, v7, v154, vcc
	v_cndmask_b32_e32 v7, v161, v151, vcc
	v_cndmask_b32_e32 v6, v182, v150, vcc
	v_cndmask_b32_e32 v5, v183, v149, vcc
	v_cndmask_b32_e32 v4, v184, v148, vcc
	v_cndmask_b32_e32 v3, v185, v147, vcc
	v_cndmask_b32_e32 v2, v186, v146, vcc
	v_mov_b64_e32 v[160:161], v[16:17]
	v_mov_b64_e32 v[158:159], v[14:15]
	v_mov_b64_e32 v[156:157], v[12:13]
	v_mov_b64_e32 v[154:155], v[10:11]
	v_mov_b64_e32 v[152:153], v[8:9]
	v_mov_b64_e32 v[150:151], v[6:7]
	v_mov_b64_e32 v[148:149], v[4:5]
	v_mov_b64_e32 v[146:147], v[2:3]

; __device__ __forceinline__ float half_max(float v) { auto rr = __builtin_amdgcn_permlane32_swap(__float_as_uint(v), __float_as_uint(v), false, false); return fmaxf(__uint_as_float(rr[0]), __uint_as_float(rr[1])); }
; __device__ __forceinline__ int crow(int r, int hi) { return (r & 3) + 8 * (r >> 2) + 4 * hi; }
; __device__ __forceinline__ void rowmax_rescale(bool MASK, f32x16& s0, f32x16 (&O)[4], float& m, float& l, int kvr, int r, int h, ATT_LAS float* wsf) {
;     ...
;     float ra = __builtin_fmaxf(__builtin_fmaxf(s0[0], s0[1]), s0[2]), rb = __builtin_fmaxf(__builtin_fmaxf(s0[3], s0[4]), s0[5]);
;     ra = __builtin_fmaxf(__builtin_fmaxf(ra, s0[6]), s0[7]); rb = __builtin_fmaxf(__builtin_fmaxf(rb, s0[8]), s0[9]);
;     ra = __builtin_fmaxf(__builtin_fmaxf(ra, s0[10]), s0[11]); rb = __builtin_fmaxf(__builtin_fmaxf(rb, s0[12]), s0[13]);
;     ra = __builtin_fmaxf(__builtin_fmaxf(ra, s0[14]), s0[15]);
;     const float rm = half_max(__builtin_fmaxf(ra, rb));
;     if (__any(rm > m + THR)) {
;         const float mn = fmaxf(m, rm), al = __builtin_amdgcn_exp2f(m - mn);
;         l *= al; m = mn;
;         if (h == 0) wsf[r] = al;
; #pragma unroll
;         for (int i = 0; i < 16; ++i) { const float a = wsf[crow(i, h)];
; #pragma unroll
;             for (int db = 0; db < 4; ++db) O[db][i] *= a; }
.LBB0_331:
	s_nop 5
	v_max_f32_e32 v2, v147, v147
	v_max_f32_e32 v3, v146, v146
	v_max_f32_e32 v2, v3, v2
	v_max3_f32 v3, v149, v150, v151
	v_max3_f32 v2, v2, v148, v152
	v_max3_f32 v3, v3, v154, v155
	v_max3_f32 v2, v2, v153, v156
	v_max3_f32 v3, v3, v158, v159
	v_max3_f32 v2, v2, v157, v160
	v_max3_f32 v2, v2, v161, v3
	v_mov_b32_e32 v3, v2
	s_nop 1
	v_permlane32_swap_b32_e32 v2, v3
	v_max_f32_e32 v3, v3, v3
	v_max_f32_e32 v2, v2, v2
	v_max_f32_e32 v2, v2, v3
	v_add_f32_e32 v3, 0x41000000, v0
	v_cmp_gt_f32_e32 vcc, v2, v3
	s_cbranch_vccz .LBB0_336
	v_max_f32_e32 v2, v2, v2
	v_max_f32_e32 v3, v0, v0
	v_max_f32_e32 v6, v3, v2
	v_cmp_gt_f32_e32 vcc, 0xf0000000, v3
	s_nop 1
	v_cndmask_b32_e64 v253, v6, 0, vcc
	v_cmp_gt_f32_e64 vcc, s100, |v2|
	s_nop 1
	v_cndmask_b32_e32 v6, v6, v253, vcc
	v_sub_f32_e32 v0, v0, v6
	v_exp_f32_e32 v0, v0
	s_and_saveexec_b64 s[6:7], s[2:3]
	ds_write_b32 v202, v0
	s_or_b64 exec, exec, s[6:7]
	v_add_u32_e32 v7, s78, v208
	ds_read_b128 v[2:5], v7 offset:96
	ds_read_b128 v[8:11], v7 offset:64
	ds_read_b128 v[12:15], v7 offset:32
	ds_read_b128 v[182:185], v7
	v_mul_f32_e32 v180, v180, v0
	s_waitcnt lgkmcnt(3)
	v_pk_mul_f32 v[46:47], v[46:47], v[2:3]
	s_waitcnt lgkmcnt(2)
	v_pk_mul_f32 v[42:43], v[42:43], v[8:9]
	s_waitcnt lgkmcnt(1)
	v_pk_mul_f32 v[38:39], v[38:39], v[12:13]
	v_pk_mul_f32 v[48:49], v[48:49], v[4:5]
	v_pk_mul_f32 v[44:45], v[44:45], v[10:11]
	v_pk_mul_f32 v[40:41], v[40:41], v[14:15]
	s_waitcnt lgkmcnt(0)
	v_pk_mul_f32 v[36:37], v[36:37], v[184:185]
	v_pk_mul_f32 v[34:35], v[34:35], v[182:183]
	v_pk_mul_f32 v[62:63], v[62:63], v[2:3]
	v_pk_mul_f32 v[58:59], v[58:59], v[8:9]
	v_pk_mul_f32 v[54:55], v[54:55], v[12:13]
	v_pk_mul_f32 v[64:65], v[64:65], v[4:5]
	v_pk_mul_f32 v[60:61], v[60:61], v[10:11]
	v_pk_mul_f32 v[56:57], v[56:57], v[14:15]
	v_pk_mul_f32 v[52:53], v[52:53], v[184:185]
	v_pk_mul_f32 v[50:51], v[50:51], v[182:183]
	v_pk_mul_f32 v[78:79], v[78:79], v[2:3]
	v_pk_mul_f32 v[74:75], v[74:75], v[8:9]
	v_pk_mul_f32 v[70:71], v[70:71], v[12:13]
	v_pk_mul_f32 v[80:81], v[80:81], v[4:5]
	v_pk_mul_f32 v[76:77], v[76:77], v[10:11]
	v_pk_mul_f32 v[72:73], v[72:73], v[14:15]
	v_pk_mul_f32 v[68:69], v[68:69], v[184:185]
	v_pk_mul_f32 v[66:67], v[66:67], v[182:183]
	v_pk_mul_f32 v[94:95], v[94:95], v[2:3]
	v_pk_mul_f32 v[90:91], v[90:91], v[8:9]
	v_pk_mul_f32 v[86:87], v[86:87], v[12:13]
	v_pk_mul_f32 v[96:97], v[96:97], v[4:5]
	v_pk_mul_f32 v[92:93], v[92:93], v[10:11]
	v_pk_mul_f32 v[88:89], v[88:89], v[14:15]
	v_pk_mul_f32 v[84:85], v[84:85], v[184:185]
	v_pk_mul_f32 v[82:83], v[82:83], v[182:183]
	s_branch .LBB0_337

; #define ATT_LAS __attribute__((address_space(3)))
; __device__ __forceinline__ int sub1(int a) { int v = a ^ 128; asm volatile("" : "+v"(v)); return v; }
; #define ATT_MFMA(a, b, c) __builtin_amdgcn_mfma_f32_32x32x16_bf16((a), (b), (c), 0, 0, 0)
; template <bool C1> __device__ __forceinline__ void qk_issue(f32x16& s0, const ATT_LAS unsigned char* kb, const ATT_LAS unsigned char* qb_, const int (&kaddr)[4]) {
; #pragma unroll
;     for (int i = 0; i < 16; ++i) s0[i] = 0.f;
; #pragma unroll
;     for (int ds = 0; ds < 4; ++ds) {
;         const int ad = C1 ? sub1(kaddr[ds]) : kaddr[ds];
;         const bf16x8 a0 = *(const ATT_LAS bf16x8*)(kb + ad);
;         const bf16x8 qv = *(const ATT_LAS bf16x8*)(qb_ + ad);
;         s0 = ATT_MFMA(a0, qv, s0);
;     }
; }
; __device__ __forceinline__ void rowmax_rescale(bool MASK, f32x16& s0, f32x16 (&O)[4], float& m, float& l, int kvr, int r, int h, ATT_LAS float* wsf) {
;     if (MASK) {
;         asm volatile("" ::: "memory");
;         const int d = r - 4 * h - kvr;
; #pragma unroll
;         for (int i = 0; i < 16; ++i) { if (((i & 3) + 8 * (i >> 2)) > d) s0[i] = -INFINITY; }
; template <bool C1> __device__ __forceinline__ void slow_step(bool MASK, f32x16& S, const ATT_LAS unsigned char* kb, const ATT_LAS unsigned char* qbase, const int (&kaddr)[4], const int (&vaddr)[2], ...
;     l = l_saved;
;     qk_issue<C1>(S, kb, qbase, kaddr);
;     rowmax_rescale(MASK, S, O, m, l, kvr, r, h, wsf);
;     f32x16 dummy;
;     step_fused<false, false, false>(S, m, l, pk, O, pk, kb, vaddr, dummy, kb, qbase, kaddr);
; }
.Lslow_4:
	v_mov_b32_e32 v6, v209
	v_mov_b32_e32 v10, v210
	v_add_u32_e32 v2, s81, v6
	ds_read_b128 v[2:5], v2 offset:8192
	v_add_u32_e32 v6, s51, v6
	ds_read_b128 v[6:9], v6
	s_and_b64 vcc, exec, s[4:5]
	v_add_u32_e32 v11, s81, v10
	s_waitcnt lgkmcnt(0)
	v_mfma_f32_32x32x16_bf16 v[146:161], v[2:5], v[6:9], 0
	ds_read_b128 v[2:5], v11 offset:8192
	v_add_u32_e32 v6, s51, v10
	ds_read_b128 v[6:9], v6
	v_mov_b32_e32 v10, v211
	s_nop 0
	v_add_u32_e32 v11, s81, v10
	s_waitcnt lgkmcnt(0)
	v_mfma_f32_32x32x16_bf16 v[146:161], v[2:5], v[6:9], v[146:161]
	ds_read_b128 v[2:5], v11 offset:8192
	v_add_u32_e32 v6, s51, v10
	ds_read_b128 v[6:9], v6
	v_mov_b32_e32 v10, v212
	s_nop 0
	v_add_u32_e32 v11, s81, v10
	s_waitcnt lgkmcnt(0)
	v_mfma_f32_32x32x16_bf16 v[146:161], v[2:5], v[6:9], v[146:161]
	ds_read_b128 v[2:5], v11 offset:8192
	v_add_u32_e32 v6, s51, v10
	ds_read_b128 v[6:9], v6
	s_waitcnt lgkmcnt(0)
	v_mfma_f32_32x32x16_bf16 v[146:161], v[2:5], v[6:9], v[146:161]
	s_cbranch_vccnz .LBB0_346
	v_subrev_u32_e32 v2, 32, v214
	v_cmp_gt_i32_e32 vcc, 27, v2
	s_and_saveexec_b64 s[34:35], vcc
	s_cbranch_execz .LBB0_345
	v_cmp_gt_i32_e32 vcc, 24, v2
	v_cmp_gt_i32_e64 s[28:29], 25, v2
	v_cmp_gt_i32_e64 s[4:5], 19, v2
	s_and_b64 vcc, s[28:29], vcc
	v_cmp_gt_i32_e64 s[6:7], 18, v2
	s_nop 1
	v_cndmask_b32_e32 v3, v158, v17, vcc
	s_and_b64 vcc, vcc, s[4:5]
	v_cmp_gt_i32_e64 s[8:9], 17, v2
	v_cndmask_b32_e32 v4, v157, v17, vcc
	s_and_b64 vcc, vcc, s[6:7]
	v_cmp_gt_i32_e64 s[10:11], 16, v2
	v_cndmask_b32_e32 v5, v156, v17, vcc
	s_and_b64 vcc, vcc, s[8:9]
	v_cmp_gt_i32_e64 s[12:13], 11, v2
	v_cndmask_b32_e32 v6, v155, v17, vcc
	s_and_b64 vcc, vcc, s[10:11]
	v_cmp_gt_i32_e64 s[14:15], 10, v2
	v_cndmask_b32_e32 v7, v154, v17, vcc
	s_and_b64 vcc, vcc, s[12:13]
	v_cmp_gt_i32_e64 s[16:17], 9, v2
	v_cndmask_b32_e32 v8, v153, v17, vcc
	s_and_b64 vcc, vcc, s[14:15]
	v_cmp_gt_i32_e64 s[18:19], 8, v2
	v_cndmask_b32_e32 v16, v152, v17, vcc
	s_and_b64 vcc, vcc, s[16:17]
	v_cmp_gt_i32_e64 s[20:21], 3, v2
	v_cndmask_b32_e32 v161, v151, v17, vcc
	s_and_b64 vcc, vcc, s[18:19]
	v_cmp_gt_i32_e64 s[22:23], 2, v2
	v_cndmask_b32_e32 v162, v150, v17, vcc
	s_and_b64 vcc, vcc, s[20:21]
	v_cmp_gt_i32_e64 s[24:25], 1, v2
	v_cndmask_b32_e32 v163, v149, v17, vcc
	s_and_b64 vcc, vcc, s[22:23]
	v_cmp_gt_i32_e64 s[26:27], 0, v2
	v_cndmask_b32_e32 v164, v148, v17, vcc
	s_and_b64 vcc, vcc, s[24:25]
	v_cndmask_b32_e32 v165, v147, v17, vcc
	s_and_b64 vcc, vcc, s[26:27]
	v_cndmask_b32_e32 v166, v146, v17, vcc
	v_cmp_eq_u32_e32 vcc, 58, v214
	v_cndmask_b32_e64 v2, v159, v17, s[28:29]
	s_nop 0
	v_cndmask_b32_e32 v9, v8, v153, vcc
	v_cndmask_b32_e32 v8, v16, v152, vcc
	v_cndmask_b32_e32 v16, v17, v160, vcc
	v_cndmask_b32_e32 v15, v2, v159, vcc
	v_cndmask_b32_e32 v14, v3, v158, vcc
	v_cndmask_b32_e32 v13, v4, v157, vcc
	v_cndmask_b32_e32 v12, v5, v156, vcc
	v_cndmask_b32_e32 v11, v6, v155, vcc
	v_cndmask_b32_e32 v10, v7, v154, vcc
	v_cndmask_b32_e32 v7, v161, v151, vcc
	v_cndmask_b32_e32 v6, v162, v150, vcc
	v_cndmask_b32_e32 v5, v163, v149, vcc
	v_cndmask_b32_e32 v4, v164, v148, vcc
	v_cndmask_b32_e32 v3, v165, v147, vcc
	v_cndmask_b32_e32 v2, v166, v146, vcc
	v_mov_b64_e32 v[160:161], v[16:17]
	v_mov_b64_e32 v[158:159], v[14:15]
	v_mov_b64_e32 v[156:157], v[12:13]
	v_mov_b64_e32 v[154:155], v[10:11]
	v_mov_b64_e32 v[152:153], v[8:9]
	v_mov_b64_e32 v[150:151], v[6:7]
	v_mov_b64_e32 v[148:149], v[4:5]
	v_mov_b64_e32 v[146:147], v[2:3]

; __device__ __forceinline__ float half_max(float v) { auto rr = __builtin_amdgcn_permlane32_swap(__float_as_uint(v), __float_as_uint(v), false, false); return fmaxf(__uint_as_float(rr[0]), __uint_as_float(rr[1])); }
; __device__ __forceinline__ int crow(int r, int hi) { return (r & 3) + 8 * (r >> 2) + 4 * hi; }
; __device__ __forceinline__ void rowmax_rescale(bool MASK, f32x16& s0, f32x16 (&O)[4], float& m, float& l, int kvr, int r, int h, ATT_LAS float* wsf) {
;     ...
;     float ra = __builtin_fmaxf(__builtin_fmaxf(s0[0], s0[1]), s0[2]), rb = __builtin_fmaxf(__builtin_fmaxf(s0[3], s0[4]), s0[5]);
;     ra = __builtin_fmaxf(__builtin_fmaxf(ra, s0[6]), s0[7]); rb = __builtin_fmaxf(__builtin_fmaxf(rb, s0[8]), s0[9]);
;     ra = __builtin_fmaxf(__builtin_fmaxf(ra, s0[10]), s0[11]); rb = __builtin_fmaxf(__builtin_fmaxf(rb, s0[12]), s0[13]);
;     ra = __builtin_fmaxf(__builtin_fmaxf(ra, s0[14]), s0[15]);
;     const float rm = half_max(__builtin_fmaxf(ra, rb));
;     if (__any(rm > m + THR)) {
;         const float mn = fmaxf(m, rm), al = __builtin_amdgcn_exp2f(m - mn);
;         l *= al; m = mn;
;         if (h == 0) wsf[r] = al;
; #pragma unroll
;         for (int i = 0; i < 16; ++i) { const float a = wsf[crow(i, h)];
; #pragma unroll
;             for (int db = 0; db < 4; ++db) O[db][i] *= a; }
.LBB0_346:
	s_nop 5
	v_max_f32_e32 v2, v147, v147
	v_max_f32_e32 v3, v146, v146
	v_max_f32_e32 v2, v3, v2
	v_max3_f32 v3, v149, v150, v151
	v_max3_f32 v2, v2, v148, v152
	v_max3_f32 v3, v3, v154, v155
	v_max3_f32 v2, v2, v153, v156
	v_max3_f32 v3, v3, v158, v159
	v_max3_f32 v2, v2, v157, v160
	v_max3_f32 v2, v2, v161, v3
	v_mov_b32_e32 v3, v2
	s_nop 1
	v_permlane32_swap_b32_e32 v2, v3
	v_max_f32_e32 v3, v3, v3
	v_max_f32_e32 v2, v2, v2
	v_max_f32_e32 v2, v2, v3
	v_add_f32_e32 v3, 0x41000000, v215
	v_cmp_gt_f32_e32 vcc, v2, v3
	s_cbranch_vccz .LBB0_350
	v_max_f32_e32 v2, v2, v2
	v_max_f32_e32 v3, v215, v215
	v_max_f32_e32 v10, v3, v2
	v_cmp_gt_f32_e32 vcc, 0xf0000000, v3
	s_nop 1
	v_cndmask_b32_e64 v253, v10, 0, vcc
	v_cmp_gt_f32_e64 vcc, s100, |v2|
	s_nop 1
	v_cndmask_b32_e32 v10, v10, v253, vcc
	v_sub_f32_e32 v2, v215, v10
	v_exp_f32_e32 v2, v2
	s_and_saveexec_b64 s[4:5], s[2:3]
	ds_write_b32 v202, v2
	s_or_b64 exec, exec, s[4:5]
	v_add_u32_e32 v3, s78, v208
	ds_read_b128 v[4:7], v3 offset:96
	ds_read_b128 v[12:15], v3 offset:64
	ds_read_b128 v[162:165], v3 offset:32
	ds_read_b128 v[166:169], v3
	v_mul_f32_e32 v181, v181, v2
	s_waitcnt lgkmcnt(3)
	v_pk_mul_f32 v[142:143], v[142:143], v[4:5]
	s_waitcnt lgkmcnt(2)
	v_pk_mul_f32 v[138:139], v[138:139], v[12:13]
	s_waitcnt lgkmcnt(1)
	v_pk_mul_f32 v[134:135], v[134:135], v[162:163]
	v_pk_mul_f32 v[144:145], v[144:145], v[6:7]
	v_pk_mul_f32 v[140:141], v[140:141], v[14:15]
	v_pk_mul_f32 v[136:137], v[136:137], v[164:165]
	s_waitcnt lgkmcnt(0)
	v_pk_mul_f32 v[132:133], v[132:133], v[168:169]
	v_pk_mul_f32 v[130:131], v[130:131], v[166:167]
	v_pk_mul_f32 v[126:127], v[126:127], v[4:5]
	v_pk_mul_f32 v[122:123], v[122:123], v[12:13]
	v_pk_mul_f32 v[118:119], v[118:119], v[162:163]
	v_pk_mul_f32 v[128:129], v[128:129], v[6:7]
	v_pk_mul_f32 v[124:125], v[124:125], v[14:15]
	v_pk_mul_f32 v[120:121], v[120:121], v[164:165]
	v_pk_mul_f32 v[116:117], v[116:117], v[168:169]
	v_pk_mul_f32 v[114:115], v[114:115], v[166:167]
	v_pk_mul_f32 v[110:111], v[110:111], v[4:5]
	v_pk_mul_f32 v[106:107], v[106:107], v[12:13]
	v_pk_mul_f32 v[102:103], v[102:103], v[162:163]
	v_pk_mul_f32 v[112:113], v[112:113], v[6:7]
	v_pk_mul_f32 v[108:109], v[108:109], v[14:15]
	v_pk_mul_f32 v[104:105], v[104:105], v[164:165]
	v_pk_mul_f32 v[100:101], v[100:101], v[168:169]
	v_pk_mul_f32 v[98:99], v[98:99], v[166:167]
	v_pk_mul_f32 v[30:31], v[30:31], v[4:5]
	v_pk_mul_f32 v[26:27], v[26:27], v[12:13]
	v_pk_mul_f32 v[22:23], v[22:23], v[162:163]
	v_pk_mul_f32 v[32:33], v[32:33], v[6:7]
	v_pk_mul_f32 v[28:29], v[28:29], v[14:15]
	v_pk_mul_f32 v[24:25], v[24:25], v[164:165]
	v_pk_mul_f32 v[20:21], v[20:21], v[168:169]
	v_pk_mul_f32 v[18:19], v[18:19], v[166:167]
	s_branch .LBB0_351

; template <bool HAS_PV, bool HAS_QK, bool C1> ...
;     s16x4 vlo[2], vhi[2]; bf16x8 ka, qa;
;     if (HAS_PV) {
; #pragma unroll
;         for (int u = 0; u < 2; ++u) { vlo[u] = vtr(vb + vaddr[0] + u * 512); vhi[u] = vtr(vb + vaddr[1] + u * 512); } }
;     if (HAS_QK) { const int ad = C1 ? sub1(kaddr[0]) : kaddr[0]; ka = *(const ATT_LAS bf16x8*)(kb + ad); qa = *(const ATT_LAS bf16x8*)(qb_ + ad);
; #pragma unroll
;         for (int i = 0; i < 16; ++i) Snext[i] = 0.f; }
;     float sa = 0.f, sb = 0.f;
; #pragma unroll
;     for (int g = 0; g < 4; ++g) {
;         s16x4 nlo[2], nhi[2]; bf16x8 nk, nq;
;         if (g < 3) {
;             if (HAS_PV) {
; #pragma unroll
;                 for (int u = 0; u < 2; ++u) { const int off = (2 * ((g + 1) & 1) + u) * 512 + ((g + 1) >> 1) * 4096; nlo[u] = vtr(vb + vaddr[0] + off); nhi[u] = vtr(vb + vaddr[1] + off); } }
;             if (HAS_QK) { const int ad = C1 ? sub1(kaddr[g + 1]) : kaddr[g + 1]; nk = *(const ATT_LAS bf16x8*)(kb + ad); nq = *(const ATT_LAS bf16x8*)(qb_ + ad); }
;         }
;         if (HAS_PV) { const bf16x8 pa = __builtin_bit_cast(bf16x8, pkin[g >> 1]);
; #pragma unroll
;             for (int u = 0; u < 2; ++u) { const bf16x8 vf = __builtin_shufflevector(vlo[u], vhi[u], 0, 1, 2, 3, 4, 5, 6, 7); Opv[2 * (g & 1) + u] = ATT_MFMA(pa, vf, Opv[2 * (g & 1) + u]); } }
;         if (HAS_QK) Snext = ATT_MFMA(ka, qa, Snext);
; #pragma unroll
;         for (int e = 4 * g; e < 4 * g + 4; e += 2) { Scur[e] = __builtin_amdgcn_exp2f(Scur[e] - m); Scur[e + 1] = __builtin_amdgcn_exp2f(Scur[e + 1] - m); sa += Scur[e]; sb += Scur[e + 1]; }
;         if (g & 1) pkout[g >> 1] = (u32x4){cvtpk(Scur[4 * g - 4], Scur[4 * g - 3]), cvtpk(Scur[4 * g - 2], Scur[4 * g - 1]), cvtpk(Scur[4 * g], Scur[4 * g + 1]), cvtpk(Scur[4 * g + 2], Scur[4 * g + 3])};
;         if (g < 3) {
;             if (HAS_PV) {
; #pragma unroll
;                 for (int u = 0; u < 2; ++u) { vlo[u] = nlo[u]; vhi[u] = nhi[u]; } }
;             if (HAS_QK) { ka = nk; qa = nq; }
;         }
;         __builtin_amdgcn_sched_barrier(0);
;     }
;     l += sa + sb;
;     return sa + sb;
; }
; __device__ __forceinline__ void tile_body(bool MASK, const ATT_LAS unsigned char* kb, const ATT_LAS unsigned char* vb, const ATT_LAS unsigned char* qbase, const int (&kaddr)[4], const int (&vaddr)[2], ...
;     ...
;     apply_mask(MASK, Sa, kvrel, r, h); ls = l1;
.Lns_296:
	ds_read_b128 v[2:5], v248
	ds_read_b128 v[6:9], v244
	s_nop 8
	ds_read_b128 v[10:13], v249
	ds_read_b128 v[146:149], v245
	v_exp_f32_e32 v15, v170
	v_mov_b32_e32 v14, v171
	v_exp_f32_e32 v155, v172
	v_mov_b32_e32 v16, v173
	s_waitcnt lgkmcnt(2)
	v_mfma_f32_32x32x16_bf16 v[158:173], v[2:5], v[6:9], 0
	v_exp_f32_e32 v14, v14
	v_exp_f32_e32 v154, v16
	s_waitcnt lgkmcnt(0)
	v_mfma_f32_32x32x16_bf16 v[158:173], v[10:13], v[146:149], v[158:173]
	ds_read_b128 v[6:9], v250
	ds_read_b128 v[150:153], v246
	v_exp_f32_e32 v157, v174
	v_exp_f32_e32 v156, v175
	v_exp_f32_e32 v175, v176
	v_exp_f32_e32 v174, v177
	v_cvt_pk_bf16_f32 v2, v15, v14
	v_cvt_pk_bf16_f32 v3, v155, v154
	v_cvt_pk_bf16_f32 v4, v157, v156
	v_cvt_pk_bf16_f32 v5, v175, v174
	s_waitcnt lgkmcnt(0)
	v_mfma_f32_32x32x16_bf16 v[158:173], v[6:9], v[150:153], v[158:173]
	ds_read_b128 v[10:13], v251
	ds_read_b128 v[146:149], v247
	v_exp_f32_e32 v177, v178
	v_exp_f32_e32 v176, v179
	v_exp_f32_e32 v179, v180
	v_exp_f32_e32 v178, v181
	s_waitcnt lgkmcnt(0)
	v_mfma_f32_32x32x16_bf16 v[158:173], v[10:13], v[146:149], v[158:173]
	v_add_f32_e64 v14, v14, 0
	v_add_f32_e64 v15, v15, 0
	v_exp_f32_e32 v7, v182
	v_pk_add_f32 v[14:15], v[154:155], v[14:15]
	v_exp_f32_e32 v6, v183
	v_exp_f32_e32 v9, v184
	v_pk_add_f32 v[14:15], v[156:157], v[14:15]
	v_exp_f32_e32 v8, v185
	v_pk_add_f32 v[14:15], v[174:175], v[14:15]
	v_cvt_pk_bf16_f32 v10, v177, v176
	v_cvt_pk_bf16_f32 v11, v179, v178
	v_cvt_pk_bf16_f32 v12, v7, v6
	v_cvt_pk_bf16_f32 v13, v9, v8
	s_nop 0
	v_pk_add_f32 v[14:15], v[176:177], v[14:15]
	s_nop 0
	v_pk_add_f32 v[14:15], v[178:179], v[14:15]
	s_nop 0
	v_pk_add_f32 v[6:7], v[6:7], v[14:15]
	s_nop 0
	v_pk_add_f32 v[6:7], v[8:9], v[6:7]
	s_nop 0
	v_add_f32_e32 v6, v6, v7
	v_cndmask_b32_e64 v7, 0, 1, s[36:37]
	v_cmp_nge_f32_e32 vcc, s58, v6
	v_cmp_ne_u32_e64 s[4:5], 1, v7
	s_cbranch_vccz .Lns_305
	s_branch .Lslow_1
.Lns_305:
	v_add_f32_e32 v180, v225, v6
	s_and_b64 vcc, exec, s[4:5]
	s_cbranch_vccz .Lns_308
	s_branch .Lns_311
.Lns_308:
	v_cmp_gt_i32_e64 s[34:35], 25, v214
	v_cmp_gt_i32_e64 s[36:37], 26, v214
	v_cmp_gt_i32_e64 s[28:29], 24, v214
	s_and_b64 s[34:35], s[36:37], s[34:35]
	v_cmp_gt_i32_e64 s[26:27], 19, v214
	s_and_b64 s[28:29], s[34:35], s[28:29]
	v_cmp_gt_i32_e64 s[24:25], 18, v214
	s_and_b64 s[26:27], s[28:29], s[26:27]
	v_cmp_gt_i32_e64 s[22:23], 17, v214
	s_and_b64 s[24:25], s[26:27], s[24:25]
	v_cmp_gt_i32_e64 s[20:21], 16, v214
	s_and_b64 s[22:23], s[24:25], s[22:23]
	v_cmp_gt_i32_e64 s[18:19], 11, v214
	s_and_b64 s[20:21], s[22:23], s[20:21]
	v_cmp_gt_i32_e64 s[16:17], 10, v214
	s_and_b64 s[18:19], s[20:21], s[18:19]
	v_cmp_gt_i32_e64 s[14:15], 9, v214
	s_and_b64 s[16:17], s[18:19], s[16:17]
	v_cmp_gt_i32_e64 s[12:13], 8, v214
	s_and_b64 s[14:15], s[16:17], s[14:15]
	v_cmp_gt_i32_e64 s[10:11], 3, v214
	s_and_b64 s[12:13], s[14:15], s[12:13]
	v_cmp_gt_i32_e64 s[8:9], 2, v214
	s_and_b64 s[10:11], s[12:13], s[10:11]
	v_cmp_gt_i32_e64 s[6:7], 1, v214
	s_and_b64 s[8:9], s[10:11], s[8:9]
	v_cmp_gt_i32_e32 vcc, 0, v214
	s_and_b64 s[6:7], s[8:9], s[6:7]
	s_and_b64 vcc, s[6:7], vcc
	v_cndmask_b32_e64 v172, v172, v17, s[36:37]
	v_cndmask_b32_e64 v171, v171, v17, s[34:35]
	v_cndmask_b32_e64 v170, v170, v17, s[28:29]
	v_cndmask_b32_e64 v169, v169, v17, s[26:27]
	v_cndmask_b32_e64 v168, v168, v17, s[24:25]
	v_cndmask_b32_e64 v167, v167, v17, s[22:23]
	v_cndmask_b32_e64 v166, v166, v17, s[20:21]
	v_cndmask_b32_e64 v165, v165, v17, s[18:19]
	v_cndmask_b32_e64 v164, v164, v17, s[16:17]
	v_cndmask_b32_e64 v163, v163, v17, s[14:15]
	v_cndmask_b32_e64 v162, v162, v17, s[12:13]
	v_cndmask_b32_e64 v161, v161, v17, s[10:11]
	v_cndmask_b32_e64 v160, v160, v17, s[8:9]
	v_cndmask_b32_e64 v159, v159, v17, s[6:7]
	v_cndmask_b32_e32 v158, v158, v17, vcc
	v_cmp_gt_i32_e32 vcc, 27, v214
	s_and_saveexec_b64 s[6:7], vcc
	v_mov_b32_e32 v173, s31
	s_or_b64 exec, exec, s[6:7]
.Lns_311:
	v_add_u32_e32 v178, s81, v213
	v_add_u32_e32 v179, s81, v207
	ds_read_b64_tr_b16 v[8:9], v178 offset:34816
	ds_read_b64_tr_b16 v[6:7], v179 offset:32768
	ds_read_b64_tr_b16 v[146:147], v179 offset:33280
	ds_read_b64_tr_b16 v[174:175], v179 offset:33792
	ds_read_b64_tr_b16 v[182:183], v179 offset:34304
	ds_read_b64_tr_b16 v[148:149], v178 offset:35328
	ds_read_b64_tr_b16 v[176:177], v178 offset:35840
	ds_read_b64_tr_b16 v[184:185], v178 offset:36352
	s_waitcnt lgkmcnt(6)
	v_mfma_f32_32x32x16_bf16 v[34:49], v[2:5], v[6:9], v[34:49]
	ds_read_b128 v[6:9], v216 offset:8192
	ds_read_b128 v[150:153], v217
	ds_read_b128 v[186:189], v218 offset:8192
	ds_read_b128 v[226:229], v219
	v_exp_f32_e32 v15, v158
	v_exp_f32_e32 v239, v160
	s_waitcnt lgkmcnt(6)
	v_mfma_f32_32x32x16_bf16 v[50:65], v[2:5], v[146:149], v[50:65]
	v_exp_f32_e32 v14, v159
	v_exp_f32_e32 v238, v161
	s_waitcnt lgkmcnt(2)
	v_mfma_f32_32x32x16_bf16 v[146:161], v[6:9], v[150:153], 0
	v_mfma_f32_32x32x16_bf16 v[66:81], v[2:5], v[174:177], v[66:81]
	ds_read_b64_tr_b16 v[6:7], v179 offset:36864
	ds_read_b64_tr_b16 v[8:9], v178 offset:38912
	ds_read_b64_tr_b16 v[176:177], v178 offset:39424
	ds_read_b64_tr_b16 v[174:175], v179 offset:37376
	ds_read_b128 v[230:233], v220 offset:8192
	ds_read_b128 v[234:237], v221
	v_exp_f32_e32 v241, v162
	v_exp_f32_e32 v240, v163
	v_mfma_f32_32x32x16_bf16 v[82:97], v[2:5], v[182:185], v[82:97]
	v_exp_f32_e32 v243, v164
	v_exp_f32_e32 v242, v165
	v_cvt_pk_bf16_f32 v2, v15, v14
	v_cvt_pk_bf16_f32 v3, v239, v238
	v_cvt_pk_bf16_f32 v4, v241, v240
	s_waitcnt lgkmcnt(6)
	v_mfma_f32_32x32x16_bf16 v[146:161], v[186:189], v[226:229], v[146:161]
	v_cvt_pk_bf16_f32 v5, v243, v242
	s_waitcnt lgkmcnt(4)
; #define ATT_LAS __attribute__((address_space(3)))
; __device__ __forceinline__ unsigned cvtpk(float lo, float hi) { unsigned r; asm volatile("v_cvt_pk_bf16_f32 %0, %1, %2" : "=v"(r) : "v"(lo), "v"(hi)); return r; }
; template <bool HAS_PV, bool HAS_QK, bool C1> ...
;     s16x4 vlo[2], vhi[2]; bf16x8 ka, qa;
;     if (HAS_PV) {
; #pragma unroll
;         for (int u = 0; u < 2; ++u) { vlo[u] = vtr(vb + vaddr[0] + u * 512); vhi[u] = vtr(vb + vaddr[1] + u * 512); } }
;     if (HAS_QK) { const int ad = C1 ? sub1(kaddr[0]) : kaddr[0]; ka = *(const ATT_LAS bf16x8*)(kb + ad); qa = *(const ATT_LAS bf16x8*)(qb_ + ad);
; #pragma unroll
;         for (int i = 0; i < 16; ++i) Snext[i] = 0.f; }
;     float sa = 0.f, sb = 0.f;
; #pragma unroll
;     for (int g = 0; g < 4; ++g) {
;         s16x4 nlo[2], nhi[2]; bf16x8 nk, nq;
;         if (g < 3) {
;             if (HAS_PV) {
; #pragma unroll
;                 for (int u = 0; u < 2; ++u) { const int off = (2 * ((g + 1) & 1) + u) * 512 + ((g + 1) >> 1) * 4096; nlo[u] = vtr(vb + vaddr[0] + off); nhi[u] = vtr(vb + vaddr[1] + off); } }
;             if (HAS_QK) { const int ad = C1 ? sub1(kaddr[g + 1]) : kaddr[g + 1]; nk = *(const ATT_LAS bf16x8*)(kb + ad); nq = *(const ATT_LAS bf16x8*)(qb_ + ad); }
;         }
;         if (HAS_PV) { const bf16x8 pa = __builtin_bit_cast(bf16x8, pkin[g >> 1]);
; #pragma unroll
;             for (int u = 0; u < 2; ++u) { const bf16x8 vf = __builtin_shufflevector(vlo[u], vhi[u], 0, 1, 2, 3, 4, 5, 6, 7); Opv[2 * (g & 1) + u] = ATT_MFMA(pa, vf, Opv[2 * (g & 1) + u]); } }
;         if (HAS_QK) Snext = ATT_MFMA(ka, qa, Snext);
; #pragma unroll
;         for (int e = 4 * g; e < 4 * g + 4; e += 2) { Scur[e] = __builtin_amdgcn_exp2f(Scur[e] - m); Scur[e + 1] = __builtin_amdgcn_exp2f(Scur[e + 1] - m); sa += Scur[e]; sb += Scur[e + 1]; }
;         if (g & 1) pkout[g >> 1] = (u32x4){cvtpk(Scur[4 * g - 4], Scur[4 * g - 3]), cvtpk(Scur[4 * g - 2], Scur[4 * g - 1]), cvtpk(Scur[4 * g], Scur[4 * g + 1]), cvtpk(Scur[4 * g + 2], Scur[4 * g + 3])};
;         if (g < 3) {
;             if (HAS_PV) {
; #pragma unroll
;                 for (int u = 0; u < 2; ++u) { vlo[u] = nlo[u]; vhi[u] = nhi[u]; } }
;             if (HAS_QK) { ka = nk; qa = nq; }
;         }
;         __builtin_amdgcn_sched_barrier(0);
;     }
;     l += sa + sb;
;     return sa + sb;
; }
	v_mfma_f32_32x32x16_bf16 v[34:49], v[10:13], v[6:9], v[34:49]
	ds_read_b64_tr_b16 v[6:7], v179 offset:37888
	ds_read_b64_tr_b16 v[8:9], v178 offset:39936
	ds_read_b64_tr_b16 v[164:165], v178 offset:40448
	ds_read_b64_tr_b16 v[162:163], v179 offset:38400
	ds_read_b128 v[182:185], v222 offset:8192
	ds_read_b128 v[186:189], v223
	s_waitcnt lgkmcnt(8)
	v_mfma_f32_32x32x16_bf16 v[50:65], v[10:13], v[174:177], v[50:65]
	v_exp_f32_e32 v175, v166
	v_exp_f32_e32 v174, v167
	v_exp_f32_e32 v167, v168
	v_exp_f32_e32 v166, v169
	s_waitcnt lgkmcnt(6)
	v_mfma_f32_32x32x16_bf16 v[146:161], v[230:233], v[234:237], v[146:161]
	s_waitcnt lgkmcnt(4)
	v_mfma_f32_32x32x16_bf16 v[66:81], v[10:13], v[6:9], v[66:81]
	v_exp_f32_e32 v169, v170
	v_exp_f32_e32 v168, v171
	v_exp_f32_e32 v171, v172
	v_exp_f32_e32 v170, v173
	s_waitcnt lgkmcnt(2)
	v_mfma_f32_32x32x16_bf16 v[82:97], v[10:13], v[162:165], v[82:97]
	v_add_f32_e64 v10, v14, 0
	v_add_f32_e64 v11, v15, 0
	v_cvt_pk_bf16_f32 v6, v175, v174
	v_cvt_pk_bf16_f32 v7, v167, v166
	v_cvt_pk_bf16_f32 v8, v169, v168
	v_cvt_pk_bf16_f32 v9, v171, v170
	v_add_f32_e64 v10, v238, v10
	v_add_f32_e64 v11, v239, v11
	s_waitcnt lgkmcnt(0)
	v_mfma_f32_32x32x16_bf16 v[146:161], v[182:185], v[186:189], v[146:161]
	v_add_f32_e64 v10, v240, v10
	v_add_f32_e64 v11, v241, v11
	v_add_f32_e64 v10, v242, v10
	v_add_f32_e64 v11, v243, v11
	v_add_f32_e64 v10, v174, v10
	v_add_f32_e64 v11, v175, v11
	v_pk_add_f32 v[10:11], v[166:167], v[10:11]
	s_nop 0
	v_pk_add_f32 v[10:11], v[168:169], v[10:11]
	s_nop 0
	v_pk_add_f32 v[10:11], v[170:171], v[10:11]
	s_nop 0
	v_add_f32_e32 v10, v10, v11
	v_cmp_nge_f32_e32 vcc, s58, v10
	s_cbranch_vccz .Lns_320
	s_branch .Lslow_2
.Lns_320:
	v_add_f32_e32 v181, v224, v10
	s_and_b64 vcc, exec, s[4:5]
	s_cbranch_vccz .Lns_323
	s_branch .Lns_326
.Lns_323:
	v_subrev_u32_e32 v10, 32, v214
	v_cmp_gt_i32_e64 s[34:35], 25, v10
	v_cmp_gt_i32_e64 s[36:37], 26, v10
	v_cmp_gt_i32_e64 s[28:29], 24, v10
	s_and_b64 s[34:35], s[36:37], s[34:35]
	v_cmp_gt_i32_e64 s[26:27], 19, v10
	s_and_b64 s[28:29], s[34:35], s[28:29]
	v_cmp_gt_i32_e64 s[24:25], 18, v10
	s_and_b64 s[26:27], s[28:29], s[26:27]
	v_cmp_gt_i32_e64 s[22:23], 17, v10
	s_and_b64 s[24:25], s[26:27], s[24:25]
	v_cmp_gt_i32_e64 s[20:21], 16, v10
	s_and_b64 s[22:23], s[24:25], s[22:23]
	v_cmp_gt_i32_e64 s[18:19], 11, v10
	s_and_b64 s[20:21], s[22:23], s[20:21]
	v_cmp_gt_i32_e64 s[16:17], 10, v10
	s_and_b64 s[18:19], s[20:21], s[18:19]
	v_cmp_gt_i32_e64 s[14:15], 9, v10
	s_and_b64 s[16:17], s[18:19], s[16:17]
	v_cmp_gt_i32_e64 s[12:13], 8, v10
	s_and_b64 s[14:15], s[16:17], s[14:15]
	v_cmp_gt_i32_e64 s[10:11], 3, v10
	s_and_b64 s[12:13], s[14:15], s[12:13]
	v_cmp_gt_i32_e64 s[8:9], 2, v10
	s_and_b64 s[10:11], s[12:13], s[10:11]
	v_cmp_gt_i32_e64 s[6:7], 1, v10
	s_and_b64 s[8:9], s[10:11], s[8:9]
	v_cmp_gt_i32_e32 vcc, 0, v10
	s_and_b64 s[6:7], s[8:9], s[6:7]
	s_and_b64 vcc, s[6:7], vcc
	v_cndmask_b32_e64 v160, v160, v17, s[36:37]
	v_cndmask_b32_e64 v159, v159, v17, s[34:35]
	v_cndmask_b32_e64 v158, v158, v17, s[28:29]
	v_cndmask_b32_e64 v157, v157, v17, s[26:27]
	v_cndmask_b32_e64 v156, v156, v17, s[24:25]
	v_cndmask_b32_e64 v155, v155, v17, s[22:23]
	v_cndmask_b32_e64 v154, v154, v17, s[20:21]
	v_cndmask_b32_e64 v153, v153, v17, s[18:19]
	v_cndmask_b32_e64 v152, v152, v17, s[16:17]
	v_cndmask_b32_e64 v151, v151, v17, s[14:15]
	v_cndmask_b32_e64 v150, v150, v17, s[12:13]
	v_cndmask_b32_e64 v149, v149, v17, s[10:11]
	v_cndmask_b32_e64 v148, v148, v17, s[8:9]
	v_cndmask_b32_e64 v147, v147, v17, s[6:7]
	v_cndmask_b32_e32 v146, v146, v17, vcc
	v_cmp_gt_i32_e32 vcc, 27, v10
	s_and_saveexec_b64 s[6:7], vcc
	v_mov_b32_e32 v161, s31
	s_or_b64 exec, exec, s[6:7]
.Lns_326:
	ds_read_b64_tr_b16 v[10:11], v179 offset:32768
	ds_read_b64_tr_b16 v[12:13], v178 offset:34816
	ds_read_b64_tr_b16 v[164:165], v178 offset:35328
	ds_read_b64_tr_b16 v[162:163], v179 offset:33280
	s_waitcnt lgkmcnt(2)
	v_mfma_f32_32x32x16_bf16 v[130:145], v[2:5], v[10:13], v[130:145]
	ds_read_b128 v[166:169], v248 offset:8192
	ds_read_b128 v[170:173], v244
	ds_read_b64_tr_b16 v[10:11], v179 offset:33792
	ds_read_b64_tr_b16 v[12:13], v178 offset:35840
	ds_read_b64_tr_b16 v[184:185], v178 offset:36352
	ds_read_b64_tr_b16 v[182:183], v179 offset:34304
	s_waitcnt lgkmcnt(6)
	v_mfma_f32_32x32x16_bf16 v[114:129], v[2:5], v[162:165], v[114:129]
	ds_read_b128 v[186:189], v249 offset:8192
	ds_read_b128 v[224:227], v245
	v_exp_f32_e32 v15, v146
	v_exp_f32_e32 v237, v148
	s_waitcnt lgkmcnt(6)
	v_mfma_f32_32x32x16_bf16 v[162:177], v[166:169], v[170:173], 0
	v_exp_f32_e32 v14, v147
	v_exp_f32_e32 v236, v149
	s_waitcnt lgkmcnt(4)
	v_mfma_f32_32x32x16_bf16 v[98:113], v[2:5], v[10:13], v[98:113]
	ds_read_b64_tr_b16 v[146:147], v179 offset:36864
	ds_read_b64_tr_b16 v[148:149], v178 offset:38912
	ds_read_b64_tr_b16 v[230:231], v178 offset:39424
	ds_read_b64_tr_b16 v[228:229], v179 offset:37376
	ds_read_b128 v[10:13], v250 offset:8192
	ds_read_b128 v[232:235], v246
	s_waitcnt lgkmcnt(8)
	v_mfma_f32_32x32x16_bf16 v[18:33], v[2:5], v[182:185], v[18:33]
	v_exp_f32_e32 v239, v150
	v_exp_f32_e32 v241, v152
	v_exp_f32_e32 v238, v151
	s_waitcnt lgkmcnt(6)
	v_mfma_f32_32x32x16_bf16 v[162:177], v[186:189], v[224:227], v[162:177]
	v_exp_f32_e32 v240, v153
	v_cvt_pk_bf16_f32 v2, v15, v14
	v_cvt_pk_bf16_f32 v3, v237, v236
	v_cvt_pk_bf16_f32 v4, v239, v238
	v_cvt_pk_bf16_f32 v5, v241, v240
	s_waitcnt lgkmcnt(4)
	v_mfma_f32_32x32x16_bf16 v[130:145], v[6:9], v[146:149], v[130:145]
	ds_read_b64_tr_b16 v[146:147], v179 offset:37888
	ds_read_b64_tr_b16 v[148:149], v178 offset:39936
	ds_read_b64_tr_b16 v[152:153], v178 offset:40448
	ds_read_b64_tr_b16 v[150:151], v179 offset:38400
	ds_read_b128 v[182:185], v251 offset:8192
	ds_read_b128 v[186:189], v247
	s_waitcnt lgkmcnt(8)
; template <bool HAS_PV, bool HAS_QK, bool C1> ...
;     s16x4 vlo[2], vhi[2]; bf16x8 ka, qa;
;     if (HAS_PV) {
; #pragma unroll
;         for (int u = 0; u < 2; ++u) { vlo[u] = vtr(vb + vaddr[0] + u * 512); vhi[u] = vtr(vb + vaddr[1] + u * 512); } }
;     if (HAS_QK) { const int ad = C1 ? sub1(kaddr[0]) : kaddr[0]; ka = *(const ATT_LAS bf16x8*)(kb + ad); qa = *(const ATT_LAS bf16x8*)(qb_ + ad);
; #pragma unroll
;         for (int i = 0; i < 16; ++i) Snext[i] = 0.f; }
;     float sa = 0.f, sb = 0.f;
; #pragma unroll
;     for (int g = 0; g < 4; ++g) {
;         s16x4 nlo[2], nhi[2]; bf16x8 nk, nq;
;         if (g < 3) {
;             if (HAS_PV) {
; #pragma unroll
;                 for (int u = 0; u < 2; ++u) { const int off = (2 * ((g + 1) & 1) + u) * 512 + ((g + 1) >> 1) * 4096; nlo[u] = vtr(vb + vaddr[0] + off); nhi[u] = vtr(vb + vaddr[1] + off); } }
;             if (HAS_QK) { const int ad = C1 ? sub1(kaddr[g + 1]) : kaddr[g + 1]; nk = *(const ATT_LAS bf16x8*)(kb + ad); nq = *(const ATT_LAS bf16x8*)(qb_ + ad); }
;         }
;         if (HAS_PV) { const bf16x8 pa = __builtin_bit_cast(bf16x8, pkin[g >> 1]);
; #pragma unroll
;             for (int u = 0; u < 2; ++u) { const bf16x8 vf = __builtin_shufflevector(vlo[u], vhi[u], 0, 1, 2, 3, 4, 5, 6, 7); Opv[2 * (g & 1) + u] = ATT_MFMA(pa, vf, Opv[2 * (g & 1) + u]); } }
;         if (HAS_QK) Snext = ATT_MFMA(ka, qa, Snext);
; #pragma unroll
;         for (int e = 4 * g; e < 4 * g + 4; e += 2) { Scur[e] = __builtin_amdgcn_exp2f(Scur[e] - m); Scur[e + 1] = __builtin_amdgcn_exp2f(Scur[e + 1] - m); sa += Scur[e]; sb += Scur[e + 1]; }
;         if (g & 1) pkout[g >> 1] = (u32x4){cvtpk(Scur[4 * g - 4], Scur[4 * g - 3]), cvtpk(Scur[4 * g - 2], Scur[4 * g - 1]), cvtpk(Scur[4 * g], Scur[4 * g + 1]), cvtpk(Scur[4 * g + 2], Scur[4 * g + 3])};
;         if (g < 3) {
;             if (HAS_PV) {
; #pragma unroll
;                 for (int u = 0; u < 2; ++u) { vlo[u] = nlo[u]; vhi[u] = nhi[u]; } }
;             if (HAS_QK) { ka = nk; qa = nq; }
;         }
;         __builtin_amdgcn_sched_barrier(0);
;     }
;     l += sa + sb;
;     return sa + sb;
; }
; __device__ __forceinline__ void tile_body(bool MASK, const ATT_LAS unsigned char* kb, const ATT_LAS unsigned char* vb, const ATT_LAS unsigned char* qbase, const int (&kaddr)[4], const int (&vaddr)[2], ...
;     ...
;     apply_mask(MASK, Sb, kvrel + 32, r, h); ls = l2;
	v_mfma_f32_32x32x16_bf16 v[114:129], v[6:9], v[228:231], v[114:129]
	v_exp_f32_e32 v225, v154
	v_exp_f32_e32 v224, v155
	v_exp_f32_e32 v155, v156
	s_waitcnt lgkmcnt(6)
	v_mfma_f32_32x32x16_bf16 v[162:177], v[10:13], v[232:235], v[162:177]
	v_exp_f32_e32 v154, v157
	v_exp_f32_e32 v157, v158
	s_waitcnt lgkmcnt(4)
	v_mfma_f32_32x32x16_bf16 v[98:113], v[6:9], v[146:149], v[98:113]
	v_exp_f32_e32 v156, v159
	v_exp_f32_e32 v147, v160
	v_exp_f32_e32 v146, v161
	v_cvt_pk_bf16_f32 v10, v225, v224
	v_cvt_pk_bf16_f32 v11, v155, v154
	s_waitcnt lgkmcnt(2)
	v_mfma_f32_32x32x16_bf16 v[18:33], v[6:9], v[150:153], v[18:33]
	v_add_f32_e64 v6, v14, 0
	v_add_f32_e64 v7, v15, 0
	v_cvt_pk_bf16_f32 v12, v157, v156
	v_cvt_pk_bf16_f32 v13, v147, v146
	v_add_f32_e64 v6, v236, v6
	v_add_f32_e64 v7, v237, v7
	v_add_f32_e64 v6, v238, v6
	v_add_f32_e64 v7, v239, v7
	s_waitcnt lgkmcnt(0)
	v_mfma_f32_32x32x16_bf16 v[162:177], v[182:185], v[186:189], v[162:177]
	v_add_f32_e64 v6, v240, v6
	v_add_f32_e64 v7, v241, v7
	v_add_f32_e64 v6, v224, v6
	v_add_f32_e64 v7, v225, v7
	v_add_f32_e64 v6, v154, v6
	v_add_f32_e64 v7, v155, v7
	v_pk_add_f32 v[6:7], v[156:157], v[6:7]
	s_nop 0
	v_pk_add_f32 v[6:7], v[146:147], v[6:7]
	s_nop 0
	v_add_f32_e32 v6, v6, v7
	v_cmp_nge_f32_e32 vcc, s58, v6
	s_cbranch_vccz .Lns_335
	s_branch .Lslow_3
.Lns_335:
	v_add_f32_e32 v225, v180, v6
	s_and_b64 vcc, exec, s[4:5]
	s_cbranch_vccz .Lns_338
	s_branch .Lns_341
.Lns_338:
	v_subrev_u32_e32 v6, 32, v214
	v_cmp_gt_i32_e64 s[34:35], 25, v6
	v_cmp_gt_i32_e64 s[36:37], 26, v6
	v_cmp_gt_i32_e64 s[28:29], 24, v6
	s_and_b64 s[34:35], s[36:37], s[34:35]
	v_cmp_gt_i32_e64 s[26:27], 19, v6
	s_and_b64 s[28:29], s[34:35], s[28:29]
	v_cmp_gt_i32_e64 s[24:25], 18, v6
	s_and_b64 s[26:27], s[28:29], s[26:27]
	v_cmp_gt_i32_e64 s[22:23], 17, v6
	s_and_b64 s[24:25], s[26:27], s[24:25]
	v_cmp_gt_i32_e64 s[20:21], 16, v6
	s_and_b64 s[22:23], s[24:25], s[22:23]
	v_cmp_gt_i32_e64 s[18:19], 11, v6
	s_and_b64 s[20:21], s[22:23], s[20:21]
	v_cmp_gt_i32_e64 s[16:17], 10, v6
	s_and_b64 s[18:19], s[20:21], s[18:19]
	v_cmp_gt_i32_e64 s[14:15], 9, v6
	s_and_b64 s[16:17], s[18:19], s[16:17]
	v_cmp_gt_i32_e64 s[12:13], 8, v6
	s_and_b64 s[14:15], s[16:17], s[14:15]
	v_cmp_gt_i32_e64 s[10:11], 3, v6
	s_and_b64 s[12:13], s[14:15], s[12:13]
	v_cmp_gt_i32_e64 s[8:9], 2, v6
	s_and_b64 s[10:11], s[12:13], s[10:11]
	v_cmp_gt_i32_e64 s[6:7], 1, v6
	s_and_b64 s[8:9], s[10:11], s[8:9]
	v_cmp_gt_i32_e32 vcc, 0, v6
	s_and_b64 s[6:7], s[8:9], s[6:7]
	s_and_b64 vcc, s[6:7], vcc
	v_cndmask_b32_e64 v176, v176, v17, s[36:37]
	v_cndmask_b32_e64 v175, v175, v17, s[34:35]
	v_cndmask_b32_e64 v174, v174, v17, s[28:29]
	v_cndmask_b32_e64 v173, v173, v17, s[26:27]
	v_cndmask_b32_e64 v172, v172, v17, s[24:25]
	v_cndmask_b32_e64 v171, v171, v17, s[22:23]
	v_cndmask_b32_e64 v170, v170, v17, s[20:21]
	v_cndmask_b32_e64 v169, v169, v17, s[18:19]
	v_cndmask_b32_e64 v168, v168, v17, s[16:17]
	v_cndmask_b32_e64 v167, v167, v17, s[14:15]
	v_cndmask_b32_e64 v166, v166, v17, s[12:13]
	v_cndmask_b32_e64 v165, v165, v17, s[10:11]
	v_cndmask_b32_e64 v164, v164, v17, s[8:9]
	v_cndmask_b32_e64 v163, v163, v17, s[6:7]
	v_cndmask_b32_e32 v162, v162, v17, vcc
	v_cmp_gt_i32_e32 vcc, 27, v6
	s_and_saveexec_b64 s[6:7], vcc
	v_mov_b32_e32 v177, s31
	s_or_b64 exec, exec, s[6:7]
.Lns_341:
	ds_read_b64_tr_b16 v[8:9], v178 offset:43008
	ds_read_b64_tr_b16 v[6:7], v179 offset:40960
	ds_read_b64_tr_b16 v[146:147], v179 offset:41472
	ds_read_b64_tr_b16 v[150:151], v179 offset:41984
	ds_read_b64_tr_b16 v[154:155], v179 offset:42496
	ds_read_b64_tr_b16 v[148:149], v178 offset:43520
	ds_read_b64_tr_b16 v[152:153], v178 offset:44032
	ds_read_b64_tr_b16 v[156:157], v178 offset:44544
	s_waitcnt lgkmcnt(6)
	v_mfma_f32_32x32x16_bf16 v[34:49], v[2:5], v[6:9], v[34:49]
	v_exp_f32_e32 v15, v162
	v_exp_f32_e32 v14, v163
	v_exp_f32_e32 v163, v164
	s_waitcnt lgkmcnt(2)
	v_mfma_f32_32x32x16_bf16 v[50:65], v[2:5], v[146:149], v[50:65]
	v_exp_f32_e32 v162, v165
	s_waitcnt lgkmcnt(1)
	v_mfma_f32_32x32x16_bf16 v[66:81], v[2:5], v[150:153], v[66:81]
	ds_read_b64_tr_b16 v[146:147], v179 offset:45056
	ds_read_b64_tr_b16 v[148:149], v178 offset:47104
	ds_read_b64_tr_b16 v[160:161], v178 offset:47616
	ds_read_b64_tr_b16 v[158:159], v179 offset:45568
	v_exp_f32_e32 v165, v166
	v_exp_f32_e32 v164, v167
	v_exp_f32_e32 v167, v168
	s_waitcnt lgkmcnt(4)
	v_mfma_f32_32x32x16_bf16 v[82:97], v[2:5], v[154:157], v[82:97]
	v_exp_f32_e32 v166, v169
	v_cvt_pk_bf16_f32 v6, v15, v14
	v_cvt_pk_bf16_f32 v7, v163, v162
	v_cvt_pk_bf16_f32 v8, v165, v164
	v_cvt_pk_bf16_f32 v9, v167, v166
	s_waitcnt lgkmcnt(2)
	v_mfma_f32_32x32x16_bf16 v[34:49], v[10:13], v[146:149], v[34:49]
	ds_read_b64_tr_b16 v[2:3], v179 offset:46080
	ds_read_b64_tr_b16 v[4:5], v178 offset:48128
	ds_read_b64_tr_b16 v[152:153], v178 offset:48640
	ds_read_b64_tr_b16 v[150:151], v179 offset:46592
	v_exp_f32_e32 v147, v170
	v_exp_f32_e32 v146, v171
	v_exp_f32_e32 v149, v172
	s_waitcnt lgkmcnt(4)
	v_mfma_f32_32x32x16_bf16 v[50:65], v[10:13], v[158:161], v[50:65]
	v_exp_f32_e32 v148, v173
	s_waitcnt lgkmcnt(2)
	v_mfma_f32_32x32x16_bf16 v[66:81], v[10:13], v[2:5], v[66:81]
	v_add_f32_e64 v14, v14, 0
	v_add_f32_e64 v15, v15, 0
	v_exp_f32_e32 v155, v174
	v_exp_f32_e32 v154, v175
	v_exp_f32_e32 v157, v176
	s_waitcnt lgkmcnt(0)
	v_mfma_f32_32x32x16_bf16 v[82:97], v[10:13], v[150:153], v[82:97]
	v_add_f32_e64 v10, v162, v14
	v_add_f32_e64 v11, v163, v15
	v_exp_f32_e32 v156, v177
	v_pk_add_f32 v[10:11], v[164:165], v[10:11]
	v_cvt_pk_bf16_f32 v2, v147, v146
	v_cvt_pk_bf16_f32 v3, v149, v148
	v_cvt_pk_bf16_f32 v4, v155, v154
	v_cvt_pk_bf16_f32 v5, v157, v156
	s_nop 0
	v_pk_add_f32 v[10:11], v[166:167], v[10:11]
	s_nop 0
	v_pk_add_f32 v[10:11], v[146:147], v[10:11]
	s_nop 0
	v_pk_add_f32 v[10:11], v[148:149], v[10:11]
	s_nop 0
	v_pk_add_f32 v[10:11], v[154:155], v[10:11]
	s_nop 0
	v_pk_add_f32 v[10:11], v[156:157], v[10:11]
	s_nop 0
	v_add_f32_e32 v10, v10, v11
	v_cmp_nge_f32_e32 vcc, s58, v10
	s_cbranch_vccz .LBB0_286
	s_branch .Lslow_4

; __global__ void __launch_bounds__(NWAVES * 64, 2) hybrid_fwd(Args a) {
	.amdhsa_kernel _Z10hybrid_fwd4Args
		.amdhsa_group_segment_fixed_size 0
		.amdhsa_private_segment_fixed_size 0
		.amdhsa_kernarg_size 400
		.amdhsa_user_sgpr_count 2
		.amdhsa_user_sgpr_dispatch_ptr 0
		.amdhsa_user_sgpr_queue_ptr 0
		.amdhsa_user_sgpr_kernarg_segment_ptr 1
		.amdhsa_user_sgpr_dispatch_id 0
		.amdhsa_user_sgpr_kernarg_preload_length 0
		.amdhsa_user_sgpr_kernarg_preload_offset 0
		.amdhsa_user_sgpr_private_segment_size 0
		.amdhsa_uses_dynamic_stack 0
		.amdhsa_enable_private_segment 0
		.amdhsa_system_sgpr_workgroup_id_x 1
		.amdhsa_system_sgpr_workgroup_id_y 0
		.amdhsa_system_sgpr_workgroup_id_z 0
		.amdhsa_system_sgpr_workgroup_info 0
		.amdhsa_system_vgpr_workitem_id 2
		.amdhsa_next_free_vgpr 256
		.amdhsa_next_free_sgpr 102
		.amdhsa_accum_offset 256
		.amdhsa_reserve_vcc 1
		.amdhsa_float_round_mode_32 0
		.amdhsa_float_round_mode_16_64 0
		.amdhsa_float_denorm_mode_32 3
		.amdhsa_float_denorm_mode_16_64 3
		.amdhsa_dx10_clamp 1
		.amdhsa_ieee_mode 1
		.amdhsa_fp16_overflow 0
		.amdhsa_tg_split 0
		.amdhsa_exception_fp_ieee_invalid_op 0
		.amdhsa_exception_fp_denorm_src 0
		.amdhsa_exception_fp_ieee_div_zero 0
		.amdhsa_exception_fp_ieee_overflow 0
		.amdhsa_exception_fp_ieee_underflow 0
		.amdhsa_exception_fp_ieee_inexact 0
		.amdhsa_exception_int_div_zero 0
	.end_amdhsa_kernel

; __global__ void __launch_bounds__(NWAVES * 64, 2) hybrid_fwd(Args a) {
amdhsa.kernels:
  - .agpr_count:     0
    .args:
      - .offset:         0
        .size:           144
        .value_kind:     by_value
      - .offset:         144
        .size:           4
        .value_kind:     hidden_block_count_x
      - .offset:         148
        .size:           4
        .value_kind:     hidden_block_count_y
      - .offset:         152
        .size:           4
        .value_kind:     hidden_block_count_z
      - .offset:         156
        .size:           2
        .value_kind:     hidden_group_size_x
      - .offset:         158
        .size:           2
        .value_kind:     hidden_group_size_y
      - .offset:         160
        .size:           2
        .value_kind:     hidden_group_size_z
      - .offset:         162
        .size:           2
        .value_kind:     hidden_remainder_x
      - .offset:         164
        .size:           2
        .value_kind:     hidden_remainder_y
      - .offset:         166
        .size:           2
        .value_kind:     hidden_remainder_z
      - .offset:         184
        .size:           8
        .value_kind:     hidden_global_offset_x
      - .offset:         192
        .size:           8
        .value_kind:     hidden_global_offset_y
      - .offset:         200
        .size:           8
        .value_kind:     hidden_global_offset_z
      - .offset:         208
        .size:           2
        .value_kind:     hidden_grid_dims
      - .offset:         232
        .size:           8
        .value_kind:     hidden_multigrid_sync_arg
      - .offset:         264
        .size:           4
        .value_kind:     hidden_dynamic_lds_size
    .group_segment_fixed_size: 0
    .kernarg_segment_align: 8
    .kernarg_segment_size: 400
    .language:       OpenCL C
    .language_version:
      - 2
      - 0
    .max_flat_workgroup_size: 512
    .name:           _Z10hybrid_fwd4Args
    .private_segment_fixed_size: 0
    .sgpr_count:     108
    .sgpr_spill_count: 17
    .symbol:         _Z10hybrid_fwd4Args.kd
    .uniform_work_group_size: 1
    .uses_dynamic_stack: false
    .vgpr_count:     256
    .vgpr_spill_count: 0
    .wavefront_size: 64
